# YN group-norm folded into G2b K loop (acc rescale at K-group boundaries, table in LDS; normalize pass only for tail rows); DTS softplus loop 5 loads in flight; carry-state copies loads up front
# speedup vs baseline: 1.0243x; 1.0104x over previous
; __device__ __forceinline__ void conv_pass(const Ctx& C_, int l) {
;     ...
;     for (int idx = gtid; idx < MREAL * NH; idx += NT) {
;         const float rw = L_DT[idx] + L_dt_bias[l * NH + (idx & 31)];
;         L_DTS[(size_t)(idx & 31) * MP + (idx >> 5)] = rw > 20.f ? rw : __logf(1.0f + __expf(rw));
;     }
.LBB0_367:
	s_mov_b32 s1, 0x3f317217
	v_mov_b32_e32 v11, 0x41b17218
	s_mov_b32 s9, 0x7f800000
	s_mov_b32 s10, 0x41a00000
	v_lshl_add_u64 v[12:13], v[6:7], 0, s[4:5]
	v_lshl_add_u64 v[14:15], v[12:13], 0, s[4:5]
	v_lshl_add_u64 v[16:17], v[14:15], 0, s[4:5]
	v_lshl_add_u64 v[18:19], v[16:17], 0, s[4:5]
	global_load_dword v10, v[2:3], off
	global_load_dword v20, v[6:7], off
	global_load_dword v21, v[12:13], off
	global_load_dword v22, v[14:15], off
	global_load_dword v23, v[16:17], off
	global_load_dword v24, v[18:19], off
	v_mov_b32_e32 v80, v114
	v_ashrrev_i32_e32 v86, 5, v80
	v_ashrrev_i32_e32 v87, 31, v86
	v_lshl_add_u64 v[86:87], v[86:87], 2, v[4:5]
	v_add_u32_e32 v81, s8, v80
	v_ashrrev_i32_e32 v88, 5, v81
	v_ashrrev_i32_e32 v89, 31, v88
	v_lshl_add_u64 v[88:89], v[88:89], 2, v[4:5]
	v_add_u32_e32 v82, s8, v81
	v_ashrrev_i32_e32 v90, 5, v82
	v_ashrrev_i32_e32 v91, 31, v90
	v_lshl_add_u64 v[90:91], v[90:91], 2, v[4:5]
	v_add_u32_e32 v83, s8, v82
	v_ashrrev_i32_e32 v92, 5, v83
	v_ashrrev_i32_e32 v93, 31, v92
	v_lshl_add_u64 v[92:93], v[92:93], 2, v[4:5]
	v_add_u32_e32 v84, s8, v83
	v_ashrrev_i32_e32 v94, 5, v84
	v_ashrrev_i32_e32 v95, 31, v94
	v_lshl_add_u64 v[94:95], v[94:95], 2, v[4:5]
	v_add_u32_e32 v114, s8, v84
	v_lshl_add_u64 v[6:7], v[18:19], 0, s[4:5]
	s_waitcnt vmcnt(0)
	v_add_f32_e32 v30, v20, v10
	v_mul_f32_e32 v40, 0x3fb8aa3b, v30
	v_exp_f32_e32 v40, v40
	s_nop 0
	v_add_f32_e32 v40, 1.0, v40
	v_cmp_gt_f32_e32 vcc, s65, v40
	s_nop 1
	v_cndmask_b32_e64 v50, 0, 32, vcc
	v_ldexp_f32 v40, v40, v50
	v_log_f32_e32 v40, v40
	v_cndmask_b32_e32 v60, 0, v11, vcc
	v_mul_f32_e32 v50, 0x3f317217, v40
	v_fma_f32 v50, v40, s1, -v50
	v_fmac_f32_e32 v50, 0x3377d1cf, v40
	v_fmac_f32_e32 v50, 0x3f317217, v40
	v_cmp_lt_f32_e64 vcc, |v40|, s9
	s_nop 1
	v_cndmask_b32_e32 v40, v40, v50, vcc
	v_sub_f32_e32 v40, v40, v60
	v_cmp_lt_f32_e32 vcc, s10, v30
	s_nop 1
	v_cndmask_b32_e32 v30, v40, v30, vcc
	global_store_dword v[86:87], v30, off
	v_add_f32_e32 v31, v21, v10
	v_mul_f32_e32 v41, 0x3fb8aa3b, v31
	v_exp_f32_e32 v41, v41
	s_nop 0
	v_add_f32_e32 v41, 1.0, v41
	v_cmp_gt_f32_e32 vcc, s65, v41
	s_nop 1
	v_cndmask_b32_e64 v51, 0, 32, vcc
	v_ldexp_f32 v41, v41, v51
	v_log_f32_e32 v41, v41
	v_cndmask_b32_e32 v61, 0, v11, vcc
	v_mul_f32_e32 v51, 0x3f317217, v41
	v_fma_f32 v51, v41, s1, -v51
	v_fmac_f32_e32 v51, 0x3377d1cf, v41
	v_fmac_f32_e32 v51, 0x3f317217, v41
	v_cmp_lt_f32_e64 vcc, |v41|, s9
	s_nop 1
	v_cndmask_b32_e32 v41, v41, v51, vcc
	v_sub_f32_e32 v41, v41, v61
	v_cmp_lt_f32_e32 vcc, s10, v31
	s_nop 1
	v_cndmask_b32_e32 v31, v41, v31, vcc
	v_cmp_gt_i32_e32 vcc, 0x89000, v81
	s_and_saveexec_b64 s[6:7], vcc
	global_store_dword v[88:89], v31, off
	s_mov_b64 exec, s[6:7]
	v_add_f32_e32 v32, v22, v10
	v_mul_f32_e32 v42, 0x3fb8aa3b, v32
	v_exp_f32_e32 v42, v42
	s_nop 0
	v_add_f32_e32 v42, 1.0, v42
	v_cmp_gt_f32_e32 vcc, s65, v42
	s_nop 1
	v_cndmask_b32_e64 v52, 0, 32, vcc
	v_ldexp_f32 v42, v42, v52
	v_log_f32_e32 v42, v42
	v_cndmask_b32_e32 v62, 0, v11, vcc
	v_mul_f32_e32 v52, 0x3f317217, v42
	v_fma_f32 v52, v42, s1, -v52
	v_fmac_f32_e32 v52, 0x3377d1cf, v42
	v_fmac_f32_e32 v52, 0x3f317217, v42
	v_cmp_lt_f32_e64 vcc, |v42|, s9
	s_nop 1
	v_cndmask_b32_e32 v42, v42, v52, vcc
	v_sub_f32_e32 v42, v42, v62
	v_cmp_lt_f32_e32 vcc, s10, v32
	s_nop 1
	v_cndmask_b32_e32 v32, v42, v32, vcc
	v_cmp_gt_i32_e32 vcc, 0x89000, v82
	s_and_saveexec_b64 s[6:7], vcc
	global_store_dword v[90:91], v32, off
	s_mov_b64 exec, s[6:7]
	v_add_f32_e32 v33, v23, v10
	v_mul_f32_e32 v43, 0x3fb8aa3b, v33
	v_exp_f32_e32 v43, v43
	s_nop 0
	v_add_f32_e32 v43, 1.0, v43
	v_cmp_gt_f32_e32 vcc, s65, v43
	s_nop 1
	v_cndmask_b32_e64 v53, 0, 32, vcc
	v_ldexp_f32 v43, v43, v53
	v_log_f32_e32 v43, v43
	v_cndmask_b32_e32 v63, 0, v11, vcc
	v_mul_f32_e32 v53, 0x3f317217, v43
	v_fma_f32 v53, v43, s1, -v53
	v_fmac_f32_e32 v53, 0x3377d1cf, v43
	v_fmac_f32_e32 v53, 0x3f317217, v43
	v_cmp_lt_f32_e64 vcc, |v43|, s9
	s_nop 1
	v_cndmask_b32_e32 v43, v43, v53, vcc
	v_sub_f32_e32 v43, v43, v63
	v_cmp_lt_f32_e32 vcc, s10, v33
	s_nop 1
	v_cndmask_b32_e32 v33, v43, v33, vcc
	v_cmp_gt_i32_e32 vcc, 0x89000, v83
	s_and_saveexec_b64 s[6:7], vcc
	global_store_dword v[92:93], v33, off
	s_mov_b64 exec, s[6:7]
	v_add_f32_e32 v34, v24, v10
	v_mul_f32_e32 v44, 0x3fb8aa3b, v34
	v_exp_f32_e32 v44, v44
	s_nop 0
	v_add_f32_e32 v44, 1.0, v44
	v_cmp_gt_f32_e32 vcc, s65, v44
	s_nop 1
	v_cndmask_b32_e64 v54, 0, 32, vcc
	v_ldexp_f32 v44, v44, v54
	v_log_f32_e32 v44, v44
	v_cndmask_b32_e32 v64, 0, v11, vcc
	v_mul_f32_e32 v54, 0x3f317217, v44
	v_fma_f32 v54, v44, s1, -v54
	v_fmac_f32_e32 v54, 0x3377d1cf, v44
	v_fmac_f32_e32 v54, 0x3f317217, v44
	v_cmp_lt_f32_e64 vcc, |v44|, s9
	s_nop 1
	v_cndmask_b32_e32 v44, v44, v54, vcc
	v_sub_f32_e32 v44, v44, v64
	v_cmp_lt_f32_e32 vcc, s10, v34
	s_nop 1
	v_cndmask_b32_e32 v34, v44, v34, vcc
	v_cmp_gt_i32_e32 vcc, 0x89000, v84
	s_and_saveexec_b64 s[6:7], vcc
	global_store_dword v[94:95], v34, off
	s_mov_b64 exec, s[6:7]
	v_cmp_gt_i32_e32 vcc, 0x89000, v114
	s_and_b64 exec, exec, vcc
	s_cbranch_execnz .LBB0_367

; __device__ __forceinline__ void row_bf16_to_f32(const bf16_t* src, float* dst, int ncol, int lane) {
;     for (int v = lane; v < ncol / 8; v += 64) { const u32x4 w = *(const u32x4*)(src + v * 8); float o[8]; unpack8(w, o);
;         *(f32x4*)(dst + v * 8) = (f32x4){o[0], o[1], o[2], o[3]}; *(f32x4*)(dst + v * 8 + 4) = (f32x4){o[4], o[5], o[6], o[7]}; }
; }
; __device__ __forceinline__ void mixer_elementwise(const Ctx& C_, int l) {
;     ...
;     for (int it = gw; it < (NBATCH + DB) * 15; it += NGW) {
;         if (it < NBATCH * 15) { const int b = it / 15, i = it - b * 15;
;             row_bf16_to_f32(L_PROJ + (size_t)(b * LP + LP - 15 + i) * NPROJ + PC_U, L_out + O_PPOOL + ((size_t)(l * NBATCH + b) * 15 + i) * 1024, 1024, lane);
;         } else { const int k = it - NBATCH * 15, b = k / 15, i = k - b * 15;
;             float* dst = L_out + O_SPOOL + ((size_t)(l * DB + b) * 15 + i) * 1024;
;             if (i < 7) row_f32_copy(L_state_pool + ((size_t)(l * DB + b) * 15 + 8 + i) * 1024, dst, 1024, lane);
;             else row_bf16_to_f32(L_PROJ + (size_t)(MPROMPT + b * DS + (i - 7)) * NPROJ + PC_U, dst, 1024, lane); }
.LBB0_554:
	v_ashrrev_i32_e32 v3, 31, v2
	s_mov_b32 s14, 0x1000
	s_mov_b32 s15, 0
	v_lshl_add_u64 v[18:19], v[2:3], 1, s[12:13]
	v_lshl_add_u64 v[22:23], v[2:3], 2, s[6:7]
	global_load_dwordx4 v[32:35], v[18:19], off
	global_load_dwordx4 v[36:39], v[18:19], off offset:1024
	s_waitcnt vmcnt(1)
	v_lshlrev_b32_e32 v64, 16, v32
	v_and_b32_e32 v65, 0xffff0000, v32
	v_lshlrev_b32_e32 v66, 16, v33
	v_and_b32_e32 v67, 0xffff0000, v33
	v_lshlrev_b32_e32 v68, 16, v34
	v_and_b32_e32 v69, 0xffff0000, v34
	v_lshlrev_b32_e32 v70, 16, v35
	v_and_b32_e32 v71, 0xffff0000, v35
	global_store_dwordx4 v[22:23], v[64:67], off
	global_store_dwordx4 v[22:23], v[68:71], off offset:16
	s_waitcnt vmcnt(2)
	v_lshlrev_b32_e32 v72, 16, v36
	v_and_b32_e32 v73, 0xffff0000, v36
	v_lshlrev_b32_e32 v74, 16, v37
	v_and_b32_e32 v75, 0xffff0000, v37
	v_lshlrev_b32_e32 v76, 16, v38
	v_and_b32_e32 v77, 0xffff0000, v38
	v_lshlrev_b32_e32 v78, 16, v39
	v_and_b32_e32 v79, 0xffff0000, v39
	global_store_dwordx4 v[22:23], v[72:75], off offset:2048
	global_store_dwordx4 v[22:23], v[76:79], off offset:2064

; __device__ __forceinline__ void row_f32_copy(const float* src, float* dst, int ncol, int lane) {
;     for (int v = lane; v < ncol / 4; v += 64) *(f32x4*)(dst + v * 4) = *(const f32x4*)(src + v * 4);
; }
; __device__ __forceinline__ void mixer_elementwise(const Ctx& C_, int l) {
;     ...
;     for (int it = gw; it < (NBATCH + DB) * 15; it += NGW) {
;         if (it < NBATCH * 15) { const int b = it / 15, i = it - b * 15;
;             row_bf16_to_f32(L_PROJ + (size_t)(b * LP + LP - 15 + i) * NPROJ + PC_U, L_out + O_PPOOL + ((size_t)(l * NBATCH + b) * 15 + i) * 1024, 1024, lane);
;         } else { const int k = it - NBATCH * 15, b = k / 15, i = k - b * 15;
;             float* dst = L_out + O_SPOOL + ((size_t)(l * DB + b) * 15 + i) * 1024;
;             if (i < 7) row_f32_copy(L_state_pool + ((size_t)(l * DB + b) * 15 + 8 + i) * 1024, dst, 1024, lane);
;             else row_bf16_to_f32(L_PROJ + (size_t)(MPROMPT + b * DS + (i - 7)) * NPROJ + PC_U, dst, 1024, lane); }
.LBB0_559:
	v_ashrrev_i32_e32 v3, 31, v2
	v_lshlrev_b64 v[18:19], 2, v[2:3]
	v_lshl_add_u64 v[20:21], s[8:9], 0, v[18:19]
	v_lshl_add_u64 v[22:23], s[6:7], 0, v[18:19]
	global_load_dwordx4 v[32:35], v[20:21], off
	global_load_dwordx4 v[36:39], v[20:21], off offset:1024
	global_load_dwordx4 v[40:43], v[20:21], off offset:2048
	global_load_dwordx4 v[44:47], v[20:21], off offset:3072
	s_waitcnt vmcnt(3)
	global_store_dwordx4 v[22:23], v[32:35], off
	s_waitcnt vmcnt(3)
	global_store_dwordx4 v[22:23], v[36:39], off offset:1024
	s_waitcnt vmcnt(3)
	global_store_dwordx4 v[22:23], v[40:43], off offset:2048
	s_waitcnt vmcnt(3)
	global_store_dwordx4 v[22:23], v[44:47], off offset:3072

; __device__ __forceinline__ void row_bf16_to_f32(const bf16_t* src, float* dst, int ncol, int lane) {
;     for (int v = lane; v < ncol / 8; v += 64) { const u32x4 w = *(const u32x4*)(src + v * 8); float o[8]; unpack8(w, o);
;         *(f32x4*)(dst + v * 8) = (f32x4){o[0], o[1], o[2], o[3]}; *(f32x4*)(dst + v * 8 + 4) = (f32x4){o[4], o[5], o[6], o[7]}; }
; }
; __device__ __forceinline__ void mixer_elementwise(const Ctx& C_, int l) {
;     ...
;     for (int it = gw; it < (NBATCH + DB) * 15; it += NGW) {
;         if (it < NBATCH * 15) { const int b = it / 15, i = it - b * 15;
;             row_bf16_to_f32(L_PROJ + (size_t)(b * LP + LP - 15 + i) * NPROJ + PC_U, L_out + O_PPOOL + ((size_t)(l * NBATCH + b) * 15 + i) * 1024, 1024, lane);
;         } else { const int k = it - NBATCH * 15, b = k / 15, i = k - b * 15;
;             float* dst = L_out + O_SPOOL + ((size_t)(l * DB + b) * 15 + i) * 1024;
;             if (i < 7) row_f32_copy(L_state_pool + ((size_t)(l * DB + b) * 15 + 8 + i) * 1024, dst, 1024, lane);
;             else row_bf16_to_f32(L_PROJ + (size_t)(MPROMPT + b * DS + (i - 7)) * NPROJ + PC_U, dst, 1024, lane); }
.LBB0_564:
	v_ashrrev_i32_e32 v3, 31, v2
	s_mov_b32 s12, 0x1000
	s_mov_b32 s13, 0
	v_lshl_add_u64 v[18:19], v[2:3], 1, s[8:9]
	v_lshl_add_u64 v[22:23], v[2:3], 2, s[10:11]
	global_load_dwordx4 v[32:35], v[18:19], off
	global_load_dwordx4 v[36:39], v[18:19], off offset:1024
	s_waitcnt vmcnt(1)
	v_lshlrev_b32_e32 v64, 16, v32
	v_and_b32_e32 v65, 0xffff0000, v32
	v_lshlrev_b32_e32 v66, 16, v33
	v_and_b32_e32 v67, 0xffff0000, v33
	v_lshlrev_b32_e32 v68, 16, v34
	v_and_b32_e32 v69, 0xffff0000, v34
	v_lshlrev_b32_e32 v70, 16, v35
	v_and_b32_e32 v71, 0xffff0000, v35
	global_store_dwordx4 v[22:23], v[64:67], off
	global_store_dwordx4 v[22:23], v[68:71], off offset:16
	s_waitcnt vmcnt(2)
	v_lshlrev_b32_e32 v72, 16, v36
	v_and_b32_e32 v73, 0xffff0000, v36
	v_lshlrev_b32_e32 v74, 16, v37
	v_and_b32_e32 v75, 0xffff0000, v37
	v_lshlrev_b32_e32 v76, 16, v38
	v_and_b32_e32 v77, 0xffff0000, v38
	v_lshlrev_b32_e32 v78, 16, v39
	v_and_b32_e32 v79, 0xffff0000, v39
	global_store_dwordx4 v[22:23], v[72:75], off offset:2048
	global_store_dwordx4 v[22:23], v[76:79], off offset:2064
	s_branch .LBB0_547

; __device__ __forceinline__ void row_bf16_to_f32(const bf16_t* src, float* dst, int ncol, int lane) {
;     for (int v = lane; v < ncol / 8; v += 64) { const u32x4 w = *(const u32x4*)(src + v * 8); float o[8]; unpack8(w, o);
;         *(f32x4*)(dst + v * 8) = (f32x4){o[0], o[1], o[2], o[3]}; *(f32x4*)(dst + v * 8 + 4) = (f32x4){o[4], o[5], o[6], o[7]}; }
; }
; __device__ __forceinline__ void mixer_elementwise(const Ctx& C_, int l) {
;     ...
;     for (int it = gw; it < (NBATCH + DB) * 3; it += NGW) {
;         if (it < NBATCH * 3) { const int b = it / 3, i = it - b * 3;
;             row_bf16_to_f32(L_PROJ + (size_t)(b * LP + LP - 3 + i) * NPROJ + PC_XBC, L_out + O_PCONV + ((size_t)(l * NBATCH + b) * 3 + i) * CONVD, CONVD, lane);
;         } else { const int k = it - NBATCH * 3, b = k / 3, i = k - b * 3;
;             row_bf16_to_f32(L_PROJ + (size_t)(MPROMPT + b * DS + 5 + i) * NPROJ + PC_XBC, L_out + O_SCONV + ((size_t)(l * DB + b) * 3 + i) * CONVD, CONVD, lane); }
;     }
.LBB0_573:
	v_ashrrev_i32_e32 v3, 31, v2
	s_mov_b32 s10, 0x1000
	s_mov_b32 s11, 0
	v_lshl_add_u64 v[18:19], v[2:3], 1, s[6:7]
	v_lshl_add_u64 v[22:23], v[2:3], 2, s[8:9]
	v_lshl_add_u64 v[20:21], v[18:19], 0, s[10:11]
	global_load_dwordx4 v[32:35], v[18:19], off
	global_load_dwordx4 v[36:39], v[18:19], off offset:1024
	global_load_dwordx4 v[40:43], v[18:19], off offset:2048
	global_load_dwordx4 v[44:47], v[18:19], off offset:3072
	global_load_dwordx4 v[48:51], v[20:21], off
	global_load_dwordx4 v[52:55], v[20:21], off offset:1024
	v_lshl_add_u64 v[24:25], v[22:23], 0, s[10:11]
	v_lshl_add_u64 v[26:27], v[24:25], 0, s[10:11]
	s_waitcnt vmcnt(5)
	v_lshlrev_b32_e32 v64, 16, v32
	v_and_b32_e32 v65, 0xffff0000, v32
	v_lshlrev_b32_e32 v66, 16, v33
	v_and_b32_e32 v67, 0xffff0000, v33
	v_lshlrev_b32_e32 v68, 16, v34
	v_and_b32_e32 v69, 0xffff0000, v34
	v_lshlrev_b32_e32 v70, 16, v35
	v_and_b32_e32 v71, 0xffff0000, v35
	global_store_dwordx4 v[22:23], v[64:67], off
	global_store_dwordx4 v[22:23], v[68:71], off offset:16
	s_waitcnt vmcnt(6)
	v_lshlrev_b32_e32 v72, 16, v36
	v_and_b32_e32 v73, 0xffff0000, v36
	v_lshlrev_b32_e32 v74, 16, v37
	v_and_b32_e32 v75, 0xffff0000, v37
	v_lshlrev_b32_e32 v76, 16, v38
	v_and_b32_e32 v77, 0xffff0000, v38
	v_lshlrev_b32_e32 v78, 16, v39
	v_and_b32_e32 v79, 0xffff0000, v39
	global_store_dwordx4 v[22:23], v[72:75], off offset:2048
	global_store_dwordx4 v[22:23], v[76:79], off offset:2064
	s_waitcnt vmcnt(7)
	v_lshlrev_b32_e32 v64, 16, v40
	v_and_b32_e32 v65, 0xffff0000, v40
	v_lshlrev_b32_e32 v66, 16, v41
	v_and_b32_e32 v67, 0xffff0000, v41
	v_lshlrev_b32_e32 v68, 16, v42
	v_and_b32_e32 v69, 0xffff0000, v42
	v_lshlrev_b32_e32 v70, 16, v43
	v_and_b32_e32 v71, 0xffff0000, v43
	global_store_dwordx4 v[24:25], v[64:67], off
	global_store_dwordx4 v[24:25], v[68:71], off offset:16
	s_waitcnt vmcnt(8)
	v_lshlrev_b32_e32 v72, 16, v44
	v_and_b32_e32 v73, 0xffff0000, v44
	v_lshlrev_b32_e32 v74, 16, v45
	v_and_b32_e32 v75, 0xffff0000, v45
	v_lshlrev_b32_e32 v76, 16, v46
	v_and_b32_e32 v77, 0xffff0000, v46
	v_lshlrev_b32_e32 v78, 16, v47
	v_and_b32_e32 v79, 0xffff0000, v47
	global_store_dwordx4 v[24:25], v[72:75], off offset:2048
	global_store_dwordx4 v[24:25], v[76:79], off offset:2064
	s_waitcnt vmcnt(9)
	v_lshlrev_b32_e32 v64, 16, v48
	v_and_b32_e32 v65, 0xffff0000, v48
	v_lshlrev_b32_e32 v66, 16, v49
	v_and_b32_e32 v67, 0xffff0000, v49
	v_lshlrev_b32_e32 v68, 16, v50
	v_and_b32_e32 v69, 0xffff0000, v50
	v_lshlrev_b32_e32 v70, 16, v51
	v_and_b32_e32 v71, 0xffff0000, v51
	global_store_dwordx4 v[26:27], v[64:67], off
	global_store_dwordx4 v[26:27], v[68:71], off offset:16
	s_waitcnt vmcnt(10)
	v_lshlrev_b32_e32 v72, 16, v52
	v_and_b32_e32 v73, 0xffff0000, v52
	v_lshlrev_b32_e32 v74, 16, v53
	v_and_b32_e32 v75, 0xffff0000, v53
	v_lshlrev_b32_e32 v76, 16, v54
	v_and_b32_e32 v77, 0xffff0000, v54
	v_lshlrev_b32_e32 v78, 16, v55
	v_and_b32_e32 v79, 0xffff0000, v55
	global_store_dwordx4 v[26:27], v[72:75], off offset:2048
	global_store_dwordx4 v[26:27], v[76:79], off offset:2064

; __device__ __forceinline__ void row_bf16_to_f32(const bf16_t* src, float* dst, int ncol, int lane) {
;     for (int v = lane; v < ncol / 8; v += 64) { const u32x4 w = *(const u32x4*)(src + v * 8); float o[8]; unpack8(w, o);
;         *(f32x4*)(dst + v * 8) = (f32x4){o[0], o[1], o[2], o[3]}; *(f32x4*)(dst + v * 8 + 4) = (f32x4){o[4], o[5], o[6], o[7]}; }
; }
; __device__ __forceinline__ void mixer_elementwise(const Ctx& C_, int l) {
;     ...
;     for (int it = gw; it < (NBATCH + DB) * 3; it += NGW) {
;         if (it < NBATCH * 3) { const int b = it / 3, i = it - b * 3;
;             row_bf16_to_f32(L_PROJ + (size_t)(b * LP + LP - 3 + i) * NPROJ + PC_XBC, L_out + O_PCONV + ((size_t)(l * NBATCH + b) * 3 + i) * CONVD, CONVD, lane);
;         } else { const int k = it - NBATCH * 3, b = k / 3, i = k - b * 3;
;             row_bf16_to_f32(L_PROJ + (size_t)(MPROMPT + b * DS + 5 + i) * NPROJ + PC_XBC, L_out + O_SCONV + ((size_t)(l * DB + b) * 3 + i) * CONVD, CONVD, lane); }
;     }
.LBB0_577:
	v_ashrrev_i32_e32 v3, 31, v2
	s_mov_b32 s10, 0x1000
	s_mov_b32 s11, 0
	v_lshl_add_u64 v[18:19], v[2:3], 1, s[6:7]
	v_lshl_add_u64 v[22:23], v[2:3], 2, s[8:9]
	v_lshl_add_u64 v[20:21], v[18:19], 0, s[10:11]
	global_load_dwordx4 v[32:35], v[18:19], off
	global_load_dwordx4 v[36:39], v[18:19], off offset:1024
	global_load_dwordx4 v[40:43], v[18:19], off offset:2048
	global_load_dwordx4 v[44:47], v[18:19], off offset:3072
	global_load_dwordx4 v[48:51], v[20:21], off
	global_load_dwordx4 v[52:55], v[20:21], off offset:1024
	v_lshl_add_u64 v[24:25], v[22:23], 0, s[10:11]
	v_lshl_add_u64 v[26:27], v[24:25], 0, s[10:11]
	s_waitcnt vmcnt(5)
	v_lshlrev_b32_e32 v64, 16, v32
	v_and_b32_e32 v65, 0xffff0000, v32
	v_lshlrev_b32_e32 v66, 16, v33
	v_and_b32_e32 v67, 0xffff0000, v33
	v_lshlrev_b32_e32 v68, 16, v34
	v_and_b32_e32 v69, 0xffff0000, v34
	v_lshlrev_b32_e32 v70, 16, v35
	v_and_b32_e32 v71, 0xffff0000, v35
	global_store_dwordx4 v[22:23], v[64:67], off
	global_store_dwordx4 v[22:23], v[68:71], off offset:16
	s_waitcnt vmcnt(6)
	v_lshlrev_b32_e32 v72, 16, v36
	v_and_b32_e32 v73, 0xffff0000, v36
	v_lshlrev_b32_e32 v74, 16, v37
	v_and_b32_e32 v75, 0xffff0000, v37
	v_lshlrev_b32_e32 v76, 16, v38
	v_and_b32_e32 v77, 0xffff0000, v38
	v_lshlrev_b32_e32 v78, 16, v39
	v_and_b32_e32 v79, 0xffff0000, v39
	global_store_dwordx4 v[22:23], v[72:75], off offset:2048
	global_store_dwordx4 v[22:23], v[76:79], off offset:2064
	s_waitcnt vmcnt(7)
	v_lshlrev_b32_e32 v64, 16, v40
	v_and_b32_e32 v65, 0xffff0000, v40
	v_lshlrev_b32_e32 v66, 16, v41
	v_and_b32_e32 v67, 0xffff0000, v41
	v_lshlrev_b32_e32 v68, 16, v42
	v_and_b32_e32 v69, 0xffff0000, v42
	v_lshlrev_b32_e32 v70, 16, v43
	v_and_b32_e32 v71, 0xffff0000, v43
	global_store_dwordx4 v[24:25], v[64:67], off
	global_store_dwordx4 v[24:25], v[68:71], off offset:16
	s_waitcnt vmcnt(8)
	v_lshlrev_b32_e32 v72, 16, v44
	v_and_b32_e32 v73, 0xffff0000, v44
	v_lshlrev_b32_e32 v74, 16, v45
	v_and_b32_e32 v75, 0xffff0000, v45
	v_lshlrev_b32_e32 v76, 16, v46
	v_and_b32_e32 v77, 0xffff0000, v46
	v_lshlrev_b32_e32 v78, 16, v47
	v_and_b32_e32 v79, 0xffff0000, v47
	global_store_dwordx4 v[24:25], v[72:75], off offset:2048
	global_store_dwordx4 v[24:25], v[76:79], off offset:2064
	s_waitcnt vmcnt(9)
	v_lshlrev_b32_e32 v64, 16, v48
	v_and_b32_e32 v65, 0xffff0000, v48
	v_lshlrev_b32_e32 v66, 16, v49
	v_and_b32_e32 v67, 0xffff0000, v49
	v_lshlrev_b32_e32 v68, 16, v50
	v_and_b32_e32 v69, 0xffff0000, v50
	v_lshlrev_b32_e32 v70, 16, v51
	v_and_b32_e32 v71, 0xffff0000, v51
	global_store_dwordx4 v[26:27], v[64:67], off
	global_store_dwordx4 v[26:27], v[68:71], off offset:16
	s_waitcnt vmcnt(10)
	v_lshlrev_b32_e32 v72, 16, v52
	v_and_b32_e32 v73, 0xffff0000, v52
	v_lshlrev_b32_e32 v74, 16, v53
	v_and_b32_e32 v75, 0xffff0000, v53
	v_lshlrev_b32_e32 v76, 16, v54
	v_and_b32_e32 v77, 0xffff0000, v54
	v_lshlrev_b32_e32 v78, 16, v55
	v_and_b32_e32 v79, 0xffff0000, v55
	global_store_dwordx4 v[26:27], v[72:75], off offset:2048
	global_store_dwordx4 v[26:27], v[76:79], off offset:2064
	s_branch .LBB0_567

; __device__ __forceinline__ KP kparams() { KP p = (KP)__builtin_amdgcn_kernarg_segment_ptr(); asm volatile("" : "+s"(p)); return p; }
; __device__ __forceinline__ void yn_normalize(const Ctx& C_) {
;     const Ctx C = get_ids(C_.wave);
;     KP kp = kparams(); unsigned char* ws = kp->ws; (void)ws;
;     bf16_t* const L_YN = (bf16_t*)(ws + WS_YN);
;     float* const L_SSQ = (float*)(ws + WS_SSQ);
;     const int gw = C.bid * NWAVES + C.wave, NGW = C.G * NWAVES, lane = C.lane;
;     for (int m = gw; m < MREAL; m += NGW) {
;         const f32x4* sp = (const f32x4*)(L_SSQ + (size_t)m * 32);
.LBB0_813:
	s_or_b64 exec, exec, s[2:3]
	s_waitcnt lgkmcnt(0)
	v_mov_b32_e32 v1, v174
	s_mov_b32 s1, s75
	s_mov_b32 s0, s74
	s_mov_b32 s4, s70
	s_barrier
	s_lshl_b32 s4, s4, 3
	v_readlane_b32 s2, v255, 3
	s_add_i32 s8, s4, s1
	s_addk_i32 s8, 0x4000
	v_readlane_b32 s3, v255, 4
	s_cmpk_gt_i32 s8, 0x447f
	s_cbranch_scc1 .LBB0_816
	s_load_dwordx2 s[10:11], s[2:3], 0xd8
	s_lshl_b32 s12, s0, 3
	v_lshlrev_b32_e32 v2, 3, v1
	s_ashr_i32 s9, s8, 31
	v_ashrrev_i32_e32 v3, 31, v2
	s_lshl_b64 s[0:1], s[8:9], 12
	s_ashr_i32 s13, s12, 31
	v_lshl_add_u64 v[2:3], v[2:3], 1, s[0:1]
	s_lshl_b64 s[14:15], s[12:13], 12
	s_lshl_b64 s[16:17], s[8:9], 7
	s_lshl_b64 s[18:19], s[12:13], 7
	s_mov_b32 s20, 0x3b000000

; #define PG8_STAGE(bufoff, gbase, voff) do { _Pragma("unroll") for (int _i = 0; _i < 2; ++_i) \
;         __builtin_amdgcn_global_load_lds((const unsigned*)((const char*)(gbase) + (voff)[_i]), (LAS unsigned*)(lds + (bufoff) + ldsw + _i * 8192), 16, 0, 0); } while (0)
; #define PG8_WAIT_V(n) asm volatile("s_waitcnt vmcnt(" #n ")" ::: "memory")
; #define PG8_BAR __builtin_amdgcn_s_barrier()
; template <class Epi>
; __device__ __forceinline__ void gemm_phase(LAS unsigned char* lds_in, int wave_in, const Gemm g, const StaticOrder& S, const Epi& E) {
;     ...
;     for (int i = 0; i < 2; ++i) { int R, C; stage_rc(tid * 16 + i * 8192, R, C); const int Rb = (R & ~31) + perm32(R & 31);
;         voffA[i] = (unsigned)(R * g.lda + C) * 2u; voffB[i] = (unsigned)(Rb * g.ldb + C) * 2u; }
;     const size_t kstep = (size_t)(BK * 2);
;     const size_t hstepA = (size_t)HALF * g.lda * 2, hstepB = (size_t)HALF * g.ldb * 2;
;     const size_t tstepA = 2 * hstepA, tstepB = 2 * hstepB;
;     const unsigned ldsw = (unsigned)wid * 1024u;
;     const int aoff = lds_byte(wr * 64 + fr, fq * 8), boff = lds_byte(wc * 32 + fr, fq * 8);
;     ...
;     Unit cur, nxt; int ui = 0;
;     if (!S.next(0, cur)) return;
;     f32x4 acc[2][2][4][2];
; #pragma unroll
;     for (int a = 0; a < 2; ++a)
; #pragma unroll
;         for (int b = 0; b < 2; ++b)
; #pragma unroll
;             for (int m = 0; m < 4; ++m)
; #pragma unroll
;                 for (int n = 0; n < 2; ++n) acc[a][b][m][n] = (f32x4){0.f, 0.f, 0.f, 0.f};
;     bf16x8 At[4][2], B0[2][2], B1[2][2];
;     const char* cA = (const char*)g.A + (size_t)cur.pm * tstepA + (size_t)cur.pn * g.a_pn_off * 2; const char* cB = (const char*)g.Bt + (size_t)cur.pn * tstepB;
;     PG8_STAGE(PG8_SB(0, 0), cB, voffB); PG8_STAGE(PG8_SB(0, 1), cB + hstepB, voffB); PG8_STAGE(PG8_SA(0, 0), cA, voffA); PG8_STAGE(PG8_SA(0, 1), cA + hstepA, voffA);
;     if (wr == 1) PG8_BAR;
;     PG8_WAIT_V(2); PG8_BAR;
;     PG8_STAGE(PG8_SB(1, 0), cB + kstep, voffB); PG8_STAGE(PG8_SA(1, 0), cA + kstep, voffA); PG8_STAGE(PG8_SB(1, 1), cB + hstepB + kstep, voffB);
;     PG8_WAIT_V(6); PG8_BAR;
.LBB0_904:
	s_sext_i32_i8 s58, s2
	v_ashrrev_i32_e32 v19, 6, v16
	s_lshl_b32 s2, s16, 5
	s_add_i32 s45, s18, 0x18000
	v_and_b32_e32 v17, 15, v16
	v_lshlrev_b32_e32 v21, 10, v19
	s_and_b32 s2, s2, 0x60
	s_add_i32 s46, s45, s3
	v_lshl_or_b32 v1, s17, 6, v17
	v_lshl_add_u32 v21, s17, 13, v21
	s_lshr_b32 s17, s2, 3
	v_lshl_add_u64 v[8:9], v[8:9], 0, s[54:55]
	s_mov_b32 m0, s46
	s_add_i32 s47, s46, 0x2000
	s_add_i32 s48, s41, 0x8000
	s_add_i32 s49, s41, 0xa000
	s_waitcnt vmcnt(2)
	s_barrier
	s_cmp_lt_u32 s16, 4
	s_cbranch_scc0 .Lynf_ld_skip
	v_readlane_b32 s80, v255, 3
	v_readlane_b32 s81, v255, 4
	s_and_b32 s82, s16, 3
	s_lshl_b32 s82, s82, 6
	s_lshl_b32 s83, s26, 8
	s_add_i32 s82, s82, s83
	s_load_dwordx2 s[80:81], s[80:81], 0xd8
	v_add_u32_e32 v120, s82, v174
	v_lshlrev_b32_e32 v120, 7, v120
	v_add_u32_e32 v120, 0x2b75c000, v120
	s_waitcnt lgkmcnt(0)
	global_load_dwordx4 v[88:91], v120, s[80:81]
	global_load_dwordx4 v[92:95], v120, s[80:81] offset:16
	global_load_dwordx4 v[96:99], v120, s[80:81] offset:32
	global_load_dwordx4 v[100:103], v120, s[80:81] offset:48
	global_load_dwordx4 v[104:107], v120, s[80:81] offset:64
	global_load_dwordx4 v[108:111], v120, s[80:81] offset:80
	global_load_dwordx4 v[112:115], v120, s[80:81] offset:96
	global_load_dwordx4 v[116:119], v120, s[80:81] offset:112
.Lynf_ld_skip:
	global_load_lds_dwordx4 v[8:9], off
	v_lshl_add_u64 v[6:7], v[6:7], 0, s[54:55]
	s_mov_b32 m0, s47
	s_add_u32 s20, s30, 0x80080
	global_load_lds_dwordx4 v[6:7], off
	v_lshl_add_u64 v[2:3], v[2:3], 0, s[54:55]
	s_mov_b32 m0, s48
	s_addc_u32 s21, s31, 0
	s_add_i32 s50, s18, 0x1c000
	global_load_lds_dwordx4 v[2:3], off
	v_lshl_add_u64 v[2:3], v[4:5], 0, s[54:55]
	s_mov_b32 m0, s49
	s_add_i32 s51, s50, s3
	global_load_lds_dwordx4 v[2:3], off
	v_lshl_add_u64 v[2:3], s[20:21], 0, v[182:183]
	s_mov_b32 m0, s51
	s_add_i32 s52, s51, 0x2000
	global_load_lds_dwordx4 v[2:3], off
	v_lshl_add_u64 v[2:3], s[20:21], 0, v[186:187]
	s_mov_b32 m0, s52
	v_ashrrev_i32_e32 v18, 1, v16
	global_load_lds_dwordx4 v[2:3], off
	v_lshlrev_b32_e32 v2, 15, v10
	v_and_b32_e32 v2, 0xffff0000, v2
	v_lshl_add_u32 v2, v11, 12, v2
	v_and_b32_e32 v3, 1, v10
	v_lshl_or_b32 v2, v3, 6, v2
	v_lshl_add_u32 v188, v12, 1, v2
	v_lshlrev_b32_e32 v2, 15, v13
	v_and_b32_e32 v20, 48, v16
	v_lshlrev_b32_e32 v16, 2, v16
	v_and_b32_e32 v2, 0xffff0000, v2
	v_lshl_or_b32 v17, v17, 6, v20
	v_and_b32_e32 v16, 32, v16
	s_waitcnt vmcnt(6)
	v_lshlrev_b32_e32 v251, 2, v1
	v_add_u32_e32 v251, 0x20000, v251
	s_cmp_lt_u32 s16, 4
	s_cbranch_scc0 .Lynf_tbl_skip
	v_add_f32_e32 v88, v88, v89
	v_add_f32_e32 v90, v90, v91
	v_add_f32_e32 v92, v92, v93
	v_add_f32_e32 v94, v94, v95
	v_add_f32_e32 v96, v96, v97
	v_add_f32_e32 v98, v98, v99
	v_add_f32_e32 v100, v100, v101
	v_add_f32_e32 v102, v102, v103
	v_add_f32_e32 v104, v104, v105
	v_add_f32_e32 v106, v106, v107
	v_add_f32_e32 v108, v108, v109
	v_add_f32_e32 v110, v110, v111
	v_add_f32_e32 v112, v112, v113
	v_add_f32_e32 v114, v114, v115
	v_add_f32_e32 v116, v116, v117
	v_add_f32_e32 v118, v118, v119
	v_add_f32_e32 v88, v88, v90
	v_add_f32_e32 v92, v92, v94
	v_add_f32_e32 v96, v96, v98
	v_add_f32_e32 v100, v100, v102
	v_add_f32_e32 v104, v104, v106
	v_add_f32_e32 v108, v108, v110
	v_add_f32_e32 v112, v112, v114
	v_add_f32_e32 v116, v116, v118
	v_add_f32_e32 v88, v88, v92
	v_add_f32_e32 v96, v96, v100
	v_add_f32_e32 v104, v104, v108
	v_add_f32_e32 v112, v112, v116
	v_fmamk_f32 v88, v88, 0x3b000000, v175
	v_fmamk_f32 v96, v96, 0x3b000000, v175
	v_fmamk_f32 v104, v104, 0x3b000000, v175
	v_fmamk_f32 v112, v112, 0x3b000000, v175
	v_rsq_f32_e32 v88, v88
	v_rsq_f32_e32 v96, v96
	v_rsq_f32_e32 v104, v104
	v_rsq_f32_e32 v112, v112
	s_and_b32 s83, s82, 0xff
	v_rcp_f32_e32 v97, v96
	v_rcp_f32_e32 v105, v104
	v_rcp_f32_e32 v113, v112
	v_add_u32_e32 v121, s83, v174
	v_lshlrev_b32_e32 v121, 2, v121
	v_add_u32_e32 v121, 0x20000, v121
	v_mul_f32_e32 v89, v88, v97
	v_mul_f32_e32 v98, v96, v105
	v_mul_f32_e32 v106, v104, v113
	ds_write_b32 v121, v89
	ds_write_b32 v121, v98 offset:1024
	ds_write_b32 v121, v106 offset:2048
	ds_write_b32 v121, v112 offset:3072
.Lynf_tbl_skip:
	v_lshl_add_u32 v2, v14, 12, v2
	v_and_b32_e32 v3, 1, v13
	v_and_b32_e32 v18, -8, v18
	v_bitop3_b32 v20, v17, v21, v16 bitop3:0xde
	v_add_lshl_u32 v19, s17, v19, 10
	s_cmp_lt_u32 s16, 4
	v_lshl_or_b32 v2, v3, 6, v2
	v_bitop3_b32 v204, v19, v17, v16 bitop3:0xf6
	s_cselect_b64 s[16:17], -1, 0
	v_add_u32_e32 v205, s2, v18
	s_ashr_i32 s56, s36, 31
	v_mov_b32_e32 v189, v0
	v_lshl_add_u32 v190, v15, 1, v2
	v_mov_b32_e32 v191, v0
	s_mov_b32 s57, 0
	v_add_u32_e32 v206, s18, v20
	s_barrier
	s_branch .LBB0_907

; #define PG8_STAGE(bufoff, gbase, voff) do { _Pragma("unroll") for (int _i = 0; _i < 2; ++_i) \
;         __builtin_amdgcn_global_load_lds((const unsigned*)((const char*)(gbase) + (voff)[_i]), (LAS unsigned*)(lds + (bufoff) + ldsw + _i * 8192), 16, 0, 0); } while (0)
; #define PG8_LDA(dst, b, h) do { _Pragma("unroll") for (int m = 0; m < 4; ++m) _Pragma("unroll") for (int k = 0; k < 2; ++k) dst[m][k] = *(const LAS bf16x8*)(lds + PG8_SA(b, h) + aoff + m * 2048 + k * 1024); } while (0)
; #define PG8_LDB(dst, b, h) do { _Pragma("unroll") for (int n = 0; n < 2; ++n) _Pragma("unroll") for (int k = 0; k < 2; ++k) dst[n][k] = *(const LAS bf16x8*)(lds + PG8_SB(b, h) + boff + n * 2048 + k * 1024); } while (0)
; #define PG8_MMA(ai, bj, At, Bt) do { __builtin_amdgcn_s_setprio(1); _Pragma("unroll") for (int m = 0; m < 4; ++m) _Pragma("unroll") for (int n = 0; n < 2; ++n) _Pragma("unroll") for (int k = 0; k < 2; ++k) \
;         acc[ai][bj][m][n] = __builtin_amdgcn_mfma_f32_16x16x32_bf16(Bt[n][k], At[m][k], acc[ai][bj][m][n], 0, 0, 0); __builtin_amdgcn_s_setprio(0); } while (0)
; #define PG8_WAIT_V(n) asm volatile("s_waitcnt vmcnt(" #n ")" ::: "memory")
; #define PG8_WAIT_L(n) asm volatile("s_waitcnt lgkmcnt(" #n ")" ::: "memory")
; #define PG8_BAR __builtin_amdgcn_s_barrier()
; #define PG8_SCHED __builtin_amdgcn_sched_barrier(0)
; template <class Epi>
; __device__ __forceinline__ void gemm_phase(LAS unsigned char* lds_in, int wave_in, const Gemm g, const StaticOrder& S, const Epi& E) {
;     ...
;             PG8_LDB(B0, 0, 0); PG8_LDB(B1, 0, 1); PG8_SCHED; PG8_LDA(At, 0, 0); PG8_STAGE(PG8_SA(1, 1), a1 + hstepA, voffA);
;             PG8_WAIT_V(8); PG8_WAIT_L(0); PG8_BAR; PG8_MMA(0, 0, At, B0); PG8_MMA(0, 1, At, B1); PG8_BAR; PG8_SCHED;
;             PG8_LDA(At, 0, 1); PG8_STAGE(PG8_SB(0, 0), b2, voffB); PG8_STAGE(PG8_SB(0, 1), b2 + hstepB, voffB); PG8_STAGE(PG8_SA(0, 0), a2, voffA);
;             PG8_WAIT_V(8); PG8_WAIT_L(0); PG8_BAR; PG8_MMA(1, 0, At, B0); PG8_MMA(1, 1, At, B1); PG8_BAR; PG8_SCHED;
.LBB0_914:
	v_add_u32_e32 v142, s0, v204
	v_add_u32_e32 v158, s33, v204
	ds_read_b128 v[130:133], v142
	ds_read_b128 v[134:137], v142 offset:1024
	ds_read_b128 v[138:141], v142 offset:2048
	ds_read_b128 v[142:145], v142 offset:3072
	ds_read_b128 v[146:149], v158
	ds_read_b128 v[150:153], v158 offset:1024
	ds_read_b128 v[154:157], v158 offset:2048
	ds_read_b128 v[158:161], v158 offset:3072
	s_add_u32 s30, s28, 0xfff80080
	s_addc_u32 s31, s29, -1
	s_cmp_eq_u32 s63, 28
	s_cselect_b32 s35, s21, s31
	s_cselect_b32 s34, s59, s30
	s_cselect_b32 s31, s19, s62
	s_cselect_b32 s30, s60, s61
	v_lshl_add_u64 v[216:217], s[28:29], 0, v[188:189]
	s_add_i32 m0, s41, 0xc000
	ds_read_b128 v[162:165], v206
	ds_read_b128 v[166:169], v206 offset:1024
	ds_read_b128 v[170:173], v206 offset:2048
	ds_read_b128 v[192:195], v206 offset:3072
	ds_read_b128 v[196:199], v206 offset:4096
	ds_read_b128 v[200:203], v206 offset:5120
	ds_read_b128 v[208:211], v206 offset:6144
	ds_read_b128 v[212:215], v206 offset:7168
	global_load_lds_dwordx4 v[216:217], off
	v_lshl_add_u64 v[216:217], s[28:29], 0, v[190:191]
	s_add_i32 m0, s41, 0xe000
	s_nop 0
	global_load_lds_dwordx4 v[216:217], off
	s_waitcnt vmcnt(8)
	s_waitcnt lgkmcnt(0)
	s_barrier
	s_setprio 1
	s_waitcnt lgkmcnt(0)
	v_mfma_f32_16x16x32_bf16 v[126:129], v[130:133], v[162:165], v[126:129]
	v_mfma_f32_16x16x32_bf16 v[122:125], v[138:141], v[162:165], v[122:125]
	v_mfma_f32_16x16x32_bf16 v[110:113], v[130:133], v[170:173], v[110:113]
	v_mfma_f32_16x16x32_bf16 v[106:109], v[138:141], v[170:173], v[106:109]
	v_mfma_f32_16x16x32_bf16 v[94:97], v[130:133], v[196:199], v[94:97]
	v_mfma_f32_16x16x32_bf16 v[90:93], v[138:141], v[196:199], v[90:93]
	v_mfma_f32_16x16x32_bf16 v[78:81], v[130:133], v[208:211], v[78:81]
	v_mfma_f32_16x16x32_bf16 v[74:77], v[138:141], v[208:211], v[74:77]
	v_mfma_f32_16x16x32_bf16 v[126:129], v[134:137], v[166:169], v[126:129]
	v_mfma_f32_16x16x32_bf16 v[122:125], v[142:145], v[166:169], v[122:125]
	v_mfma_f32_16x16x32_bf16 v[110:113], v[134:137], v[192:195], v[110:113]
	v_mfma_f32_16x16x32_bf16 v[106:109], v[142:145], v[192:195], v[106:109]
	v_mfma_f32_16x16x32_bf16 v[94:97], v[134:137], v[200:203], v[94:97]
	v_mfma_f32_16x16x32_bf16 v[90:93], v[142:145], v[200:203], v[90:93]
	v_mfma_f32_16x16x32_bf16 v[78:81], v[134:137], v[212:215], v[78:81]
	v_mfma_f32_16x16x32_bf16 v[74:77], v[142:145], v[212:215], v[74:77]
	s_setprio 0
	s_setprio 1
	v_mfma_f32_16x16x32_bf16 v[118:121], v[146:149], v[162:165], v[118:121]
	v_mfma_f32_16x16x32_bf16 v[114:117], v[154:157], v[162:165], v[114:117]
	v_mfma_f32_16x16x32_bf16 v[102:105], v[146:149], v[170:173], v[102:105]
	v_mfma_f32_16x16x32_bf16 v[98:101], v[154:157], v[170:173], v[98:101]
	v_mfma_f32_16x16x32_bf16 v[86:89], v[146:149], v[196:199], v[86:89]
	v_mfma_f32_16x16x32_bf16 v[82:85], v[154:157], v[196:199], v[82:85]
	v_mfma_f32_16x16x32_bf16 v[70:73], v[146:149], v[208:211], v[70:73]
	v_mfma_f32_16x16x32_bf16 v[66:69], v[154:157], v[208:211], v[66:69]
	v_mfma_f32_16x16x32_bf16 v[118:121], v[150:153], v[166:169], v[118:121]
	v_mfma_f32_16x16x32_bf16 v[114:117], v[158:161], v[166:169], v[114:117]
	v_mfma_f32_16x16x32_bf16 v[102:105], v[150:153], v[192:195], v[102:105]
	v_mfma_f32_16x16x32_bf16 v[98:101], v[158:161], v[192:195], v[98:101]
	v_mfma_f32_16x16x32_bf16 v[86:89], v[150:153], v[200:203], v[86:89]
	v_mfma_f32_16x16x32_bf16 v[82:85], v[158:161], v[200:203], v[82:85]
	v_mfma_f32_16x16x32_bf16 v[70:73], v[150:153], v[212:215], v[70:73]
	v_mfma_f32_16x16x32_bf16 v[66:69], v[158:161], v[212:215], v[66:69]
	s_setprio 0
	s_barrier
	s_mov_b32 m0, s1
	v_lshl_add_u64 v[216:217], s[30:31], 0, v[182:183]
	s_add_u32 s64, s30, 0x80000
	ds_read_b128 v[162:165], v206 offset:16384
	ds_read_b128 v[166:169], v206 offset:17408
	ds_read_b128 v[170:173], v206 offset:18432
	ds_read_b128 v[192:195], v206 offset:19456
	ds_read_b128 v[196:199], v206 offset:20480
	ds_read_b128 v[200:203], v206 offset:21504
	ds_read_b128 v[208:211], v206 offset:22528
	ds_read_b128 v[212:215], v206 offset:23552
	global_load_lds_dwordx4 v[216:217], off
	v_lshl_add_u64 v[218:219], s[30:31], 0, v[186:187]
	s_mov_b32 m0, s27
	s_addc_u32 s65, s31, 0
	global_load_lds_dwordx4 v[218:219], off
	v_lshl_add_u64 v[220:221], s[64:65], 0, v[182:183]
	s_mov_b32 m0, s39
	v_lshl_add_u64 v[222:223], s[34:35], 0, v[184:185]
	global_load_lds_dwordx4 v[220:221], off
	v_lshl_add_u64 v[220:221], s[64:65], 0, v[186:187]
	s_mov_b32 m0, s40
	s_nop 0
	global_load_lds_dwordx4 v[220:221], off
	v_lshl_add_u64 v[220:221], s[34:35], 0, v[180:181]
	s_mov_b32 m0, s41
	s_nop 0
	global_load_lds_dwordx4 v[220:221], off
	s_mov_b32 m0, s42
	s_nop 0
	global_load_lds_dwordx4 v[222:223], off
	s_waitcnt vmcnt(8)
	s_waitcnt lgkmcnt(0)
	s_barrier
; #define PG8_STAGE(bufoff, gbase, voff) do { _Pragma("unroll") for (int _i = 0; _i < 2; ++_i) \
;         __builtin_amdgcn_global_load_lds((const unsigned*)((const char*)(gbase) + (voff)[_i]), (LAS unsigned*)(lds + (bufoff) + ldsw + _i * 8192), 16, 0, 0); } while (0)
; #define PG8_LDA(dst, b, h) do { _Pragma("unroll") for (int m = 0; m < 4; ++m) _Pragma("unroll") for (int k = 0; k < 2; ++k) dst[m][k] = *(const LAS bf16x8*)(lds + PG8_SA(b, h) + aoff + m * 2048 + k * 1024); } while (0)
; #define PG8_LDB(dst, b, h) do { _Pragma("unroll") for (int n = 0; n < 2; ++n) _Pragma("unroll") for (int k = 0; k < 2; ++k) dst[n][k] = *(const LAS bf16x8*)(lds + PG8_SB(b, h) + boff + n * 2048 + k * 1024); } while (0)
; #define PG8_MMA(ai, bj, At, Bt) do { __builtin_amdgcn_s_setprio(1); _Pragma("unroll") for (int m = 0; m < 4; ++m) _Pragma("unroll") for (int n = 0; n < 2; ++n) _Pragma("unroll") for (int k = 0; k < 2; ++k) \
;         acc[ai][bj][m][n] = __builtin_amdgcn_mfma_f32_16x16x32_bf16(Bt[n][k], At[m][k], acc[ai][bj][m][n], 0, 0, 0); __builtin_amdgcn_s_setprio(0); } while (0)
; #define PG8_WAIT_V(n) asm volatile("s_waitcnt vmcnt(" #n ")" ::: "memory")
; #define PG8_WAIT_L(n) asm volatile("s_waitcnt lgkmcnt(" #n ")" ::: "memory")
; #define PG8_BAR __builtin_amdgcn_s_barrier()
; #define PG8_SCHED __builtin_amdgcn_sched_barrier(0)
; template <class Epi>
; __device__ __forceinline__ void gemm_phase(LAS unsigned char* lds_in, int wave_in, const Gemm g, const StaticOrder& S, const Epi& E) {
;     ...
;             PG8_WAIT_V(8); PG8_WAIT_L(0); PG8_BAR; PG8_MMA(1, 0, At, B0); PG8_MMA(1, 1, At, B1); PG8_BAR; PG8_SCHED;
;             PG8_LDB(B0, 1, 0); PG8_LDB(B1, 1, 1); PG8_SCHED; PG8_LDA(At, 1, 0); PG8_STAGE(PG8_SA(0, 1), a2 + hstepA, voffA);
;             PG8_WAIT_V(8); PG8_WAIT_L(0); PG8_BAR; PG8_MMA(0, 0, At, B0); PG8_MMA(0, 1, At, B1); PG8_BAR; PG8_SCHED;
	s_setprio 1
	s_waitcnt lgkmcnt(0)
	v_mfma_f32_16x16x32_bf16 v[62:65], v[130:133], v[162:165], v[62:65]
	v_mfma_f32_16x16x32_bf16 v[58:61], v[138:141], v[162:165], v[58:61]
	v_mfma_f32_16x16x32_bf16 v[46:49], v[130:133], v[170:173], v[46:49]
	v_mfma_f32_16x16x32_bf16 v[42:45], v[138:141], v[170:173], v[42:45]
	v_mfma_f32_16x16x32_bf16 v[30:33], v[130:133], v[196:199], v[30:33]
	v_mfma_f32_16x16x32_bf16 v[26:29], v[138:141], v[196:199], v[26:29]
	v_mfma_f32_16x16x32_bf16 v[14:17], v[130:133], v[208:211], v[14:17]
	v_mfma_f32_16x16x32_bf16 v[10:13], v[138:141], v[208:211], v[10:13]
	v_mfma_f32_16x16x32_bf16 v[62:65], v[134:137], v[166:169], v[62:65]
	v_mfma_f32_16x16x32_bf16 v[58:61], v[142:145], v[166:169], v[58:61]
	v_mfma_f32_16x16x32_bf16 v[46:49], v[134:137], v[192:195], v[46:49]
	v_mfma_f32_16x16x32_bf16 v[42:45], v[142:145], v[192:195], v[42:45]
	v_mfma_f32_16x16x32_bf16 v[30:33], v[134:137], v[200:203], v[30:33]
	v_mfma_f32_16x16x32_bf16 v[26:29], v[142:145], v[200:203], v[26:29]
	v_mfma_f32_16x16x32_bf16 v[14:17], v[134:137], v[212:215], v[14:17]
	v_mfma_f32_16x16x32_bf16 v[10:13], v[142:145], v[212:215], v[10:13]
	s_setprio 0
	s_setprio 1
	v_mfma_f32_16x16x32_bf16 v[54:57], v[146:149], v[162:165], v[54:57]
	v_mfma_f32_16x16x32_bf16 v[50:53], v[154:157], v[162:165], v[50:53]
	v_mfma_f32_16x16x32_bf16 v[38:41], v[146:149], v[170:173], v[38:41]
	v_mfma_f32_16x16x32_bf16 v[34:37], v[154:157], v[170:173], v[34:37]
	v_mfma_f32_16x16x32_bf16 v[22:25], v[146:149], v[196:199], v[22:25]
	v_mfma_f32_16x16x32_bf16 v[18:21], v[154:157], v[196:199], v[18:21]
	v_mfma_f32_16x16x32_bf16 v[6:9], v[146:149], v[208:211], v[6:9]
	v_mfma_f32_16x16x32_bf16 v[2:5], v[154:157], v[208:211], v[2:5]
	v_mfma_f32_16x16x32_bf16 v[54:57], v[150:153], v[166:169], v[54:57]
	v_mfma_f32_16x16x32_bf16 v[50:53], v[158:161], v[166:169], v[50:53]
	v_mfma_f32_16x16x32_bf16 v[38:41], v[150:153], v[192:195], v[38:41]
	v_mfma_f32_16x16x32_bf16 v[34:37], v[158:161], v[192:195], v[34:37]
	v_mfma_f32_16x16x32_bf16 v[22:25], v[150:153], v[200:203], v[22:25]
	v_mfma_f32_16x16x32_bf16 v[18:21], v[158:161], v[200:203], v[18:21]
	v_mfma_f32_16x16x32_bf16 v[6:9], v[150:153], v[212:215], v[6:9]
	v_mfma_f32_16x16x32_bf16 v[2:5], v[158:161], v[212:215], v[2:5]
	s_setprio 0
	s_barrier
	v_add_u32_e32 v142, s45, v204
	v_add_u32_e32 v158, s50, v204
	ds_read_b128 v[130:133], v142
	ds_read_b128 v[134:137], v142 offset:1024
	ds_read_b128 v[138:141], v142 offset:2048
	ds_read_b128 v[142:145], v142 offset:3072
	ds_read_b128 v[146:149], v158
	ds_read_b128 v[150:153], v158 offset:1024
	ds_read_b128 v[154:157], v158 offset:2048
	ds_read_b128 v[158:161], v158 offset:3072
	s_add_u32 s34, s34, 0x80000
	s_addc_u32 s35, s35, 0
	s_mov_b32 m0, s43
	v_lshl_add_u64 v[224:225], s[34:35], 0, v[180:181]
	ds_read_b128 v[162:165], v206 offset:32768
	ds_read_b128 v[166:169], v206 offset:33792
	ds_read_b128 v[170:173], v206 offset:34816
	ds_read_b128 v[192:195], v206 offset:35840
	ds_read_b128 v[196:199], v206 offset:36864
	ds_read_b128 v[200:203], v206 offset:37888
	ds_read_b128 v[208:211], v206 offset:38912
	ds_read_b128 v[212:215], v206 offset:39936
	global_load_lds_dwordx4 v[224:225], off
	v_lshl_add_u64 v[224:225], s[34:35], 0, v[184:185]
	s_mov_b32 m0, s44
	s_nop 0
	global_load_lds_dwordx4 v[224:225], off
	s_waitcnt vmcnt(8)
	s_waitcnt lgkmcnt(0)
	s_barrier
	s_setprio 1
	s_waitcnt lgkmcnt(0)
	v_mfma_f32_16x16x32_bf16 v[126:129], v[130:133], v[162:165], v[126:129]
	v_mfma_f32_16x16x32_bf16 v[122:125], v[138:141], v[162:165], v[122:125]
	v_mfma_f32_16x16x32_bf16 v[110:113], v[130:133], v[170:173], v[110:113]
	v_mfma_f32_16x16x32_bf16 v[106:109], v[138:141], v[170:173], v[106:109]
	v_mfma_f32_16x16x32_bf16 v[94:97], v[130:133], v[196:199], v[94:97]
	v_mfma_f32_16x16x32_bf16 v[90:93], v[138:141], v[196:199], v[90:93]
	v_mfma_f32_16x16x32_bf16 v[78:81], v[130:133], v[208:211], v[78:81]
	v_mfma_f32_16x16x32_bf16 v[74:77], v[138:141], v[208:211], v[74:77]
	v_mfma_f32_16x16x32_bf16 v[126:129], v[134:137], v[166:169], v[126:129]
	v_mfma_f32_16x16x32_bf16 v[122:125], v[142:145], v[166:169], v[122:125]
	v_mfma_f32_16x16x32_bf16 v[110:113], v[134:137], v[192:195], v[110:113]
	v_mfma_f32_16x16x32_bf16 v[106:109], v[142:145], v[192:195], v[106:109]
	v_mfma_f32_16x16x32_bf16 v[94:97], v[134:137], v[200:203], v[94:97]
	v_mfma_f32_16x16x32_bf16 v[90:93], v[142:145], v[200:203], v[90:93]
	v_mfma_f32_16x16x32_bf16 v[78:81], v[134:137], v[212:215], v[78:81]
	v_mfma_f32_16x16x32_bf16 v[74:77], v[142:145], v[212:215], v[74:77]
	s_setprio 0
	s_setprio 1
	v_mfma_f32_16x16x32_bf16 v[118:121], v[146:149], v[162:165], v[118:121]
	v_mfma_f32_16x16x32_bf16 v[114:117], v[154:157], v[162:165], v[114:117]
	v_mfma_f32_16x16x32_bf16 v[102:105], v[146:149], v[170:173], v[102:105]
	v_mfma_f32_16x16x32_bf16 v[98:101], v[154:157], v[170:173], v[98:101]
	v_mfma_f32_16x16x32_bf16 v[86:89], v[146:149], v[196:199], v[86:89]
	v_mfma_f32_16x16x32_bf16 v[82:85], v[154:157], v[196:199], v[82:85]
	v_mfma_f32_16x16x32_bf16 v[70:73], v[146:149], v[208:211], v[70:73]
	v_mfma_f32_16x16x32_bf16 v[66:69], v[154:157], v[208:211], v[66:69]
	v_mfma_f32_16x16x32_bf16 v[118:121], v[150:153], v[166:169], v[118:121]
	v_mfma_f32_16x16x32_bf16 v[114:117], v[158:161], v[166:169], v[114:117]
	v_mfma_f32_16x16x32_bf16 v[102:105], v[150:153], v[192:195], v[102:105]
	v_mfma_f32_16x16x32_bf16 v[98:101], v[158:161], v[192:195], v[98:101]
	v_mfma_f32_16x16x32_bf16 v[86:89], v[150:153], v[200:203], v[86:89]
	v_mfma_f32_16x16x32_bf16 v[82:85], v[158:161], v[200:203], v[82:85]
	v_mfma_f32_16x16x32_bf16 v[70:73], v[150:153], v[212:215], v[70:73]
	v_mfma_f32_16x16x32_bf16 v[66:69], v[158:161], v[212:215], v[66:69]
	s_setprio 0
	s_barrier
; #define PG8_STAGE(bufoff, gbase, voff) do { _Pragma("unroll") for (int _i = 0; _i < 2; ++_i) \
;         __builtin_amdgcn_global_load_lds((const unsigned*)((const char*)(gbase) + (voff)[_i]), (LAS unsigned*)(lds + (bufoff) + ldsw + _i * 8192), 16, 0, 0); } while (0)
; #define PG8_LDA(dst, b, h) do { _Pragma("unroll") for (int m = 0; m < 4; ++m) _Pragma("unroll") for (int k = 0; k < 2; ++k) dst[m][k] = *(const LAS bf16x8*)(lds + PG8_SA(b, h) + aoff + m * 2048 + k * 1024); } while (0)
; #define PG8_MMA(ai, bj, At, Bt) do { __builtin_amdgcn_s_setprio(1); _Pragma("unroll") for (int m = 0; m < 4; ++m) _Pragma("unroll") for (int n = 0; n < 2; ++n) _Pragma("unroll") for (int k = 0; k < 2; ++k) \
;         acc[ai][bj][m][n] = __builtin_amdgcn_mfma_f32_16x16x32_bf16(Bt[n][k], At[m][k], acc[ai][bj][m][n], 0, 0, 0); __builtin_amdgcn_s_setprio(0); } while (0)
; #define PG8_WAIT_V(n) asm volatile("s_waitcnt vmcnt(" #n ")" ::: "memory")
; #define PG8_WAIT_L(n) asm volatile("s_waitcnt lgkmcnt(" #n ")" ::: "memory")
; #define PG8_BAR __builtin_amdgcn_s_barrier()
; #define PG8_SCHED __builtin_amdgcn_sched_barrier(0)
; template <class Epi>
; __device__ __forceinline__ void gemm_phase(LAS unsigned char* lds_in, int wave_in, const Gemm g, const StaticOrder& S, const Epi& E) {
;     ...
;             PG8_LDA(At, 1, 1); PG8_STAGE(PG8_SB(1, 0), b3, voffB); PG8_STAGE(PG8_SB(1, 1), b3 + hstepB, voffB); PG8_STAGE(PG8_SA(1, 0), a3, voffA);
;             PG8_WAIT_V(8); PG8_WAIT_L(0); PG8_BAR; PG8_MMA(1, 0, At, B0); PG8_MMA(1, 1, At, B1); PG8_BAR; PG8_SCHED;
;         }
	s_mov_b32 m0, s46
	v_lshl_add_u64 v[216:217], v[216:217], 0, s[54:55]
	s_add_u32 s30, s30, 0x80080
	ds_read_b128 v[162:165], v206 offset:49152
	ds_read_b128 v[166:169], v206 offset:50176
	ds_read_b128 v[170:173], v206 offset:51200
	ds_read_b128 v[192:195], v206 offset:52224
	ds_read_b128 v[196:199], v206 offset:53248
	ds_read_b128 v[200:203], v206 offset:54272
	ds_read_b128 v[208:211], v206 offset:55296
	ds_read_b128 v[212:215], v206 offset:56320
	global_load_lds_dwordx4 v[216:217], off
	v_lshl_add_u64 v[216:217], v[218:219], 0, s[54:55]
	s_mov_b32 m0, s47
	s_addc_u32 s31, s31, 0
	global_load_lds_dwordx4 v[216:217], off
	v_lshl_add_u64 v[216:217], s[30:31], 0, v[182:183]
	s_mov_b32 m0, s51
	s_nop 0
	global_load_lds_dwordx4 v[216:217], off
	v_lshl_add_u64 v[216:217], s[30:31], 0, v[186:187]
	s_mov_b32 m0, s52
	s_nop 0
	global_load_lds_dwordx4 v[216:217], off
	v_lshl_add_u64 v[216:217], v[220:221], 0, s[54:55]
	s_mov_b32 m0, s48
	s_nop 0
	global_load_lds_dwordx4 v[216:217], off
	v_lshl_add_u64 v[216:217], v[222:223], 0, s[54:55]
	s_mov_b32 m0, s49
	s_nop 0
	global_load_lds_dwordx4 v[216:217], off
	s_waitcnt vmcnt(8)
	s_waitcnt lgkmcnt(0)
	s_barrier
	s_setprio 1
	s_waitcnt lgkmcnt(0)
	v_mfma_f32_16x16x32_bf16 v[62:65], v[130:133], v[162:165], v[62:65]
	v_mfma_f32_16x16x32_bf16 v[58:61], v[138:141], v[162:165], v[58:61]
	v_mfma_f32_16x16x32_bf16 v[46:49], v[130:133], v[170:173], v[46:49]
	v_mfma_f32_16x16x32_bf16 v[42:45], v[138:141], v[170:173], v[42:45]
	v_mfma_f32_16x16x32_bf16 v[30:33], v[130:133], v[196:199], v[30:33]
	v_mfma_f32_16x16x32_bf16 v[26:29], v[138:141], v[196:199], v[26:29]
	v_mfma_f32_16x16x32_bf16 v[14:17], v[130:133], v[208:211], v[14:17]
	v_mfma_f32_16x16x32_bf16 v[10:13], v[138:141], v[208:211], v[10:13]
	v_mfma_f32_16x16x32_bf16 v[62:65], v[134:137], v[166:169], v[62:65]
	v_mfma_f32_16x16x32_bf16 v[58:61], v[142:145], v[166:169], v[58:61]
	v_mfma_f32_16x16x32_bf16 v[46:49], v[134:137], v[192:195], v[46:49]
	v_mfma_f32_16x16x32_bf16 v[42:45], v[142:145], v[192:195], v[42:45]
	v_mfma_f32_16x16x32_bf16 v[30:33], v[134:137], v[200:203], v[30:33]
	v_mfma_f32_16x16x32_bf16 v[26:29], v[142:145], v[200:203], v[26:29]
	v_mfma_f32_16x16x32_bf16 v[14:17], v[134:137], v[212:215], v[14:17]
	v_mfma_f32_16x16x32_bf16 v[10:13], v[142:145], v[212:215], v[10:13]
	s_setprio 0
	s_setprio 1
	v_mfma_f32_16x16x32_bf16 v[54:57], v[146:149], v[162:165], v[54:57]
	v_mfma_f32_16x16x32_bf16 v[50:53], v[154:157], v[162:165], v[50:53]
	v_mfma_f32_16x16x32_bf16 v[38:41], v[146:149], v[170:173], v[38:41]
	v_mfma_f32_16x16x32_bf16 v[34:37], v[154:157], v[170:173], v[34:37]
	v_mfma_f32_16x16x32_bf16 v[22:25], v[146:149], v[196:199], v[22:25]
	v_mfma_f32_16x16x32_bf16 v[18:21], v[154:157], v[196:199], v[18:21]
	v_mfma_f32_16x16x32_bf16 v[6:9], v[146:149], v[208:211], v[6:9]
	v_mfma_f32_16x16x32_bf16 v[2:5], v[154:157], v[208:211], v[2:5]
	v_mfma_f32_16x16x32_bf16 v[54:57], v[150:153], v[166:169], v[54:57]
	v_mfma_f32_16x16x32_bf16 v[50:53], v[158:161], v[166:169], v[50:53]
	v_mfma_f32_16x16x32_bf16 v[38:41], v[150:153], v[192:195], v[38:41]
	v_mfma_f32_16x16x32_bf16 v[34:37], v[158:161], v[192:195], v[34:37]
	v_mfma_f32_16x16x32_bf16 v[22:25], v[150:153], v[200:203], v[22:25]
	v_mfma_f32_16x16x32_bf16 v[18:21], v[158:161], v[200:203], v[18:21]
	v_mfma_f32_16x16x32_bf16 v[6:9], v[150:153], v[212:215], v[6:9]
	v_mfma_f32_16x16x32_bf16 v[2:5], v[158:161], v[212:215], v[2:5]
	s_setprio 0
	s_barrier
	s_add_i32 s63, s63, 2
	s_add_u32 s28, s28, 0x100
	s_addc_u32 s29, s29, 0
	s_add_u32 s61, s61, 0x100
	s_addc_u32 s62, s62, 0
	s_and_b32 s82, s63, 7
	s_cmp_eq_u32 s82, 6
	s_cbranch_scc0 .Lynf_noscale
; #define PG8_BAR __builtin_amdgcn_s_barrier()
; template <class Epi>
; __device__ __forceinline__ void gemm_phase(LAS unsigned char* lds_in, int wave_in, const Gemm g, const StaticOrder& S, const Epi& E) {
;     ...
;         }
;         if (wr == 0) PG8_BAR;
	s_lshr_b32 s82, s63, 3
	s_lshl_b32 s82, s82, 10
	v_add_u32_e32 v252, s82, v251
	ds_read_b32 v230, v252
	ds_read_b32 v235, v252 offset:64
	ds_read_b32 v240, v252 offset:128
	ds_read_b32 v241, v252 offset:192
	ds_read_b32 v242, v252 offset:512
	ds_read_b32 v248, v252 offset:576
	ds_read_b32 v249, v252 offset:640
	ds_read_b32 v250, v252 offset:704
	s_waitcnt lgkmcnt(0)
	v_mul_f32_e32 v114, v230, v114
	v_mul_f32_e32 v115, v230, v115
	v_mul_f32_e32 v116, v230, v116
	v_mul_f32_e32 v117, v230, v117
	v_mul_f32_e32 v118, v230, v118
	v_mul_f32_e32 v119, v230, v119
	v_mul_f32_e32 v120, v230, v120
	v_mul_f32_e32 v121, v230, v121
	v_mul_f32_e32 v122, v230, v122
	v_mul_f32_e32 v123, v230, v123
	v_mul_f32_e32 v124, v230, v124
	v_mul_f32_e32 v125, v230, v125
	v_mul_f32_e32 v126, v230, v126
	v_mul_f32_e32 v127, v230, v127
	v_mul_f32_e32 v128, v230, v128
	v_mul_f32_e32 v129, v230, v129
	v_mul_f32_e32 v98, v235, v98
	v_mul_f32_e32 v99, v235, v99
	v_mul_f32_e32 v100, v235, v100
	v_mul_f32_e32 v101, v235, v101
	v_mul_f32_e32 v102, v235, v102
	v_mul_f32_e32 v103, v235, v103
	v_mul_f32_e32 v104, v235, v104
	v_mul_f32_e32 v105, v235, v105
	v_mul_f32_e32 v106, v235, v106
	v_mul_f32_e32 v107, v235, v107
	v_mul_f32_e32 v108, v235, v108
	v_mul_f32_e32 v109, v235, v109
	v_mul_f32_e32 v110, v235, v110
	v_mul_f32_e32 v111, v235, v111
	v_mul_f32_e32 v112, v235, v112
	v_mul_f32_e32 v113, v235, v113
	v_mul_f32_e32 v82, v240, v82
	v_mul_f32_e32 v83, v240, v83
	v_mul_f32_e32 v84, v240, v84
	v_mul_f32_e32 v85, v240, v85
	v_mul_f32_e32 v86, v240, v86
	v_mul_f32_e32 v87, v240, v87
	v_mul_f32_e32 v88, v240, v88
	v_mul_f32_e32 v89, v240, v89
	v_mul_f32_e32 v90, v240, v90
	v_mul_f32_e32 v91, v240, v91
	v_mul_f32_e32 v92, v240, v92
	v_mul_f32_e32 v93, v240, v93
	v_mul_f32_e32 v94, v240, v94
	v_mul_f32_e32 v95, v240, v95
	v_mul_f32_e32 v96, v240, v96
	v_mul_f32_e32 v97, v240, v97
	v_mul_f32_e32 v66, v241, v66
	v_mul_f32_e32 v67, v241, v67
	v_mul_f32_e32 v68, v241, v68
	v_mul_f32_e32 v69, v241, v69
	v_mul_f32_e32 v70, v241, v70
	v_mul_f32_e32 v71, v241, v71
	v_mul_f32_e32 v72, v241, v72
	v_mul_f32_e32 v73, v241, v73
	v_mul_f32_e32 v74, v241, v74
	v_mul_f32_e32 v75, v241, v75
	v_mul_f32_e32 v76, v241, v76
	v_mul_f32_e32 v77, v241, v77
	v_mul_f32_e32 v78, v241, v78
	v_mul_f32_e32 v79, v241, v79
	v_mul_f32_e32 v80, v241, v80
	v_mul_f32_e32 v81, v241, v81
	v_mul_f32_e32 v50, v242, v50
	v_mul_f32_e32 v51, v242, v51
	v_mul_f32_e32 v52, v242, v52
	v_mul_f32_e32 v53, v242, v53
	v_mul_f32_e32 v54, v242, v54
	v_mul_f32_e32 v55, v242, v55
	v_mul_f32_e32 v56, v242, v56
	v_mul_f32_e32 v57, v242, v57
	v_mul_f32_e32 v58, v242, v58
	v_mul_f32_e32 v59, v242, v59
	v_mul_f32_e32 v60, v242, v60
	v_mul_f32_e32 v61, v242, v61
	v_mul_f32_e32 v62, v242, v62
	v_mul_f32_e32 v63, v242, v63
	v_mul_f32_e32 v64, v242, v64
	v_mul_f32_e32 v65, v242, v65
	v_mul_f32_e32 v34, v248, v34
	v_mul_f32_e32 v35, v248, v35
	v_mul_f32_e32 v36, v248, v36
	v_mul_f32_e32 v37, v248, v37
	v_mul_f32_e32 v38, v248, v38
	v_mul_f32_e32 v39, v248, v39
	v_mul_f32_e32 v40, v248, v40
	v_mul_f32_e32 v41, v248, v41
	v_mul_f32_e32 v42, v248, v42
	v_mul_f32_e32 v43, v248, v43
	v_mul_f32_e32 v44, v248, v44
	v_mul_f32_e32 v45, v248, v45
	v_mul_f32_e32 v46, v248, v46
	v_mul_f32_e32 v47, v248, v47
	v_mul_f32_e32 v48, v248, v48
	v_mul_f32_e32 v49, v248, v49
	v_mul_f32_e32 v18, v249, v18
	v_mul_f32_e32 v19, v249, v19
	v_mul_f32_e32 v20, v249, v20
	v_mul_f32_e32 v21, v249, v21
	v_mul_f32_e32 v22, v249, v22
	v_mul_f32_e32 v23, v249, v23
	v_mul_f32_e32 v24, v249, v24
	v_mul_f32_e32 v25, v249, v25
	v_mul_f32_e32 v26, v249, v26
	v_mul_f32_e32 v27, v249, v27
	v_mul_f32_e32 v28, v249, v28
	v_mul_f32_e32 v29, v249, v29
	v_mul_f32_e32 v30, v249, v30
	v_mul_f32_e32 v31, v249, v31
	v_mul_f32_e32 v32, v249, v32
	v_mul_f32_e32 v33, v249, v33
	v_mul_f32_e32 v2, v250, v2
	v_mul_f32_e32 v3, v250, v3
	v_mul_f32_e32 v4, v250, v4
	v_mul_f32_e32 v5, v250, v5
	v_mul_f32_e32 v6, v250, v6
	v_mul_f32_e32 v7, v250, v7
	v_mul_f32_e32 v8, v250, v8
	v_mul_f32_e32 v9, v250, v9
	v_mul_f32_e32 v10, v250, v10
	v_mul_f32_e32 v11, v250, v11
	v_mul_f32_e32 v12, v250, v12
	v_mul_f32_e32 v13, v250, v13
	v_mul_f32_e32 v14, v250, v14
	v_mul_f32_e32 v15, v250, v15
	v_mul_f32_e32 v16, v250, v16
	v_mul_f32_e32 v17, v250, v17
.Lynf_noscale:
	s_cmp_gt_u32 s63, 29
	s_cbranch_scc0 .LBB0_914
	s_and_b64 vcc, exec, s[16:17]
	s_cbranch_vccz .LBB0_917
	s_barrier

; __device__ __forceinline__ void row_bf16_to_f32(const bf16_t* src, float* dst, int ncol, int lane) {
;     for (int v = lane; v < ncol / 8; v += 64) { const u32x4 w = *(const u32x4*)(src + v * 8); float o[8]; unpack8(w, o);
;         *(f32x4*)(dst + v * 8) = (f32x4){o[0], o[1], o[2], o[3]}; *(f32x4*)(dst + v * 8 + 4) = (f32x4){o[4], o[5], o[6], o[7]}; }
; }
; __device__ __forceinline__ void ffn_elementwise(const Ctx& C_, int l) {
;     ...
;     const int gw = C.bid * NWAVES + C.wave, NGW = C.G * NWAVES, lane = C.lane;
;     for (int it = gw; it < (NBATCH + DB) * 2; it += NGW) {
;         if (it < NBATCH * 2) { const int b = it / 2, i = it - b * 2;
;             row_bf16_to_f32(L_UP + (size_t)(b * LP + LP - 2 + i) * DUP, L_out + O_PFFN + ((size_t)(l * NBATCH + b) * 2 + i) * DUP, DUP, lane);
;         } else { const int k = it - NBATCH * 2, b = k / 2, i = k - b * 2;
;             row_bf16_to_f32(L_UP + (size_t)(MPROMPT + b * DS + 6 + i) * DUP, L_out + O_SFFN + ((size_t)(l * DB + b) * 2 + i) * DUP, DUP, lane); }
;     }
.LBB0_1181:
	v_ashrrev_i32_e32 v3, 31, v2
	s_mov_b32 s12, 0x1000
	s_mov_b32 s13, 0
	v_lshl_add_u64 v[6:7], v[2:3], 1, s[8:9]
	v_lshl_add_u64 v[14:15], v[2:3], 2, s[10:11]
	v_lshl_add_u64 v[16:17], v[6:7], 0, s[12:13]
	v_lshl_add_u64 v[18:19], v[16:17], 0, s[12:13]
	global_load_dwordx4 v[20:23], v[6:7], off
	global_load_dwordx4 v[24:27], v[6:7], off offset:1024
	global_load_dwordx4 v[28:31], v[6:7], off offset:2048
	global_load_dwordx4 v[32:35], v[6:7], off offset:3072
	global_load_dwordx4 v[36:39], v[16:17], off
	global_load_dwordx4 v[40:43], v[16:17], off offset:1024
	global_load_dwordx4 v[44:47], v[16:17], off offset:2048
	global_load_dwordx4 v[48:51], v[16:17], off offset:3072
	global_load_dwordx4 v[52:55], v[18:19], off
	global_load_dwordx4 v[56:59], v[18:19], off offset:1024
	global_load_dwordx4 v[60:63], v[18:19], off offset:2048
	v_lshl_add_u64 v[64:65], v[14:15], 0, s[12:13]
	v_lshl_add_u64 v[66:67], v[64:65], 0, s[12:13]
	v_lshl_add_u64 v[68:69], v[66:67], 0, s[12:13]
	v_lshl_add_u64 v[70:71], v[68:69], 0, s[12:13]
	v_lshl_add_u64 v[72:73], v[70:71], 0, s[12:13]
	s_waitcnt vmcnt(10)
	v_lshlrev_b32_e32 v76, 16, v20
	v_and_b32_e32 v77, 0xffff0000, v20
	v_lshlrev_b32_e32 v78, 16, v21
	v_and_b32_e32 v79, 0xffff0000, v21
	v_lshlrev_b32_e32 v80, 16, v22
	v_and_b32_e32 v81, 0xffff0000, v22
	v_lshlrev_b32_e32 v82, 16, v23
	v_and_b32_e32 v83, 0xffff0000, v23
	global_store_dwordx4 v[14:15], v[76:79], off
	global_store_dwordx4 v[14:15], v[80:83], off offset:16
	s_waitcnt vmcnt(11)
	v_lshlrev_b32_e32 v84, 16, v24
	v_and_b32_e32 v85, 0xffff0000, v24
	v_lshlrev_b32_e32 v86, 16, v25
	v_and_b32_e32 v87, 0xffff0000, v25
	v_lshlrev_b32_e32 v88, 16, v26
	v_and_b32_e32 v89, 0xffff0000, v26
	v_lshlrev_b32_e32 v90, 16, v27
	v_and_b32_e32 v91, 0xffff0000, v27
	global_store_dwordx4 v[14:15], v[84:87], off offset:2048
	global_store_dwordx4 v[14:15], v[88:91], off offset:2064
	s_waitcnt vmcnt(12)
	v_lshlrev_b32_e32 v76, 16, v28
	v_and_b32_e32 v77, 0xffff0000, v28
	v_lshlrev_b32_e32 v78, 16, v29
	v_and_b32_e32 v79, 0xffff0000, v29
	v_lshlrev_b32_e32 v80, 16, v30
	v_and_b32_e32 v81, 0xffff0000, v30
	v_lshlrev_b32_e32 v82, 16, v31
	v_and_b32_e32 v83, 0xffff0000, v31
	global_store_dwordx4 v[64:65], v[76:79], off
	global_store_dwordx4 v[64:65], v[80:83], off offset:16
	s_waitcnt vmcnt(13)
	v_lshlrev_b32_e32 v84, 16, v32
	v_and_b32_e32 v85, 0xffff0000, v32
	v_lshlrev_b32_e32 v86, 16, v33
	v_and_b32_e32 v87, 0xffff0000, v33
	v_lshlrev_b32_e32 v88, 16, v34
	v_and_b32_e32 v89, 0xffff0000, v34
	v_lshlrev_b32_e32 v90, 16, v35
	v_and_b32_e32 v91, 0xffff0000, v35
	global_store_dwordx4 v[64:65], v[84:87], off offset:2048
	global_store_dwordx4 v[64:65], v[88:91], off offset:2064
	s_waitcnt vmcnt(14)
	v_lshlrev_b32_e32 v76, 16, v36
	v_and_b32_e32 v77, 0xffff0000, v36
	v_lshlrev_b32_e32 v78, 16, v37
	v_and_b32_e32 v79, 0xffff0000, v37
	v_lshlrev_b32_e32 v80, 16, v38
	v_and_b32_e32 v81, 0xffff0000, v38
	v_lshlrev_b32_e32 v82, 16, v39
	v_and_b32_e32 v83, 0xffff0000, v39
	global_store_dwordx4 v[66:67], v[76:79], off
	global_store_dwordx4 v[66:67], v[80:83], off offset:16
	s_waitcnt vmcnt(15)
	v_lshlrev_b32_e32 v84, 16, v40
	v_and_b32_e32 v85, 0xffff0000, v40
	v_lshlrev_b32_e32 v86, 16, v41
	v_and_b32_e32 v87, 0xffff0000, v41
	v_lshlrev_b32_e32 v88, 16, v42
	v_and_b32_e32 v89, 0xffff0000, v42
	v_lshlrev_b32_e32 v90, 16, v43
	v_and_b32_e32 v91, 0xffff0000, v43
	global_store_dwordx4 v[66:67], v[84:87], off offset:2048
	global_store_dwordx4 v[66:67], v[88:91], off offset:2064
	s_waitcnt vmcnt(16)
	v_lshlrev_b32_e32 v76, 16, v44
	v_and_b32_e32 v77, 0xffff0000, v44
	v_lshlrev_b32_e32 v78, 16, v45
	v_and_b32_e32 v79, 0xffff0000, v45
	v_lshlrev_b32_e32 v80, 16, v46
	v_and_b32_e32 v81, 0xffff0000, v46
	v_lshlrev_b32_e32 v82, 16, v47
	v_and_b32_e32 v83, 0xffff0000, v47
	global_store_dwordx4 v[68:69], v[76:79], off
	global_store_dwordx4 v[68:69], v[80:83], off offset:16
	s_waitcnt vmcnt(17)
	v_lshlrev_b32_e32 v84, 16, v48
	v_and_b32_e32 v85, 0xffff0000, v48
	v_lshlrev_b32_e32 v86, 16, v49
	v_and_b32_e32 v87, 0xffff0000, v49
	v_lshlrev_b32_e32 v88, 16, v50
	v_and_b32_e32 v89, 0xffff0000, v50
	v_lshlrev_b32_e32 v90, 16, v51
	v_and_b32_e32 v91, 0xffff0000, v51
	global_store_dwordx4 v[68:69], v[84:87], off offset:2048
	global_store_dwordx4 v[68:69], v[88:91], off offset:2064
	s_waitcnt vmcnt(18)
	v_lshlrev_b32_e32 v76, 16, v52
	v_and_b32_e32 v77, 0xffff0000, v52
	v_lshlrev_b32_e32 v78, 16, v53
	v_and_b32_e32 v79, 0xffff0000, v53
	v_lshlrev_b32_e32 v80, 16, v54
	v_and_b32_e32 v81, 0xffff0000, v54
	v_lshlrev_b32_e32 v82, 16, v55
	v_and_b32_e32 v83, 0xffff0000, v55
	global_store_dwordx4 v[70:71], v[76:79], off
	global_store_dwordx4 v[70:71], v[80:83], off offset:16
	s_waitcnt vmcnt(19)
	v_lshlrev_b32_e32 v84, 16, v56
	v_and_b32_e32 v85, 0xffff0000, v56
	v_lshlrev_b32_e32 v86, 16, v57
	v_and_b32_e32 v87, 0xffff0000, v57
	v_lshlrev_b32_e32 v88, 16, v58
	v_and_b32_e32 v89, 0xffff0000, v58
	v_lshlrev_b32_e32 v90, 16, v59
	v_and_b32_e32 v91, 0xffff0000, v59
	global_store_dwordx4 v[70:71], v[84:87], off offset:2048
	global_store_dwordx4 v[70:71], v[88:91], off offset:2064
	s_waitcnt vmcnt(20)
	v_lshlrev_b32_e32 v76, 16, v60
	v_and_b32_e32 v77, 0xffff0000, v60
	v_lshlrev_b32_e32 v78, 16, v61
	v_and_b32_e32 v79, 0xffff0000, v61
	v_lshlrev_b32_e32 v80, 16, v62
	v_and_b32_e32 v81, 0xffff0000, v62
	v_lshlrev_b32_e32 v82, 16, v63
	v_and_b32_e32 v83, 0xffff0000, v63
	global_store_dwordx4 v[72:73], v[76:79], off
	global_store_dwordx4 v[72:73], v[80:83], off offset:16

; __device__ __forceinline__ void row_bf16_to_f32(const bf16_t* src, float* dst, int ncol, int lane) {
;     for (int v = lane; v < ncol / 8; v += 64) { const u32x4 w = *(const u32x4*)(src + v * 8); float o[8]; unpack8(w, o);
;         *(f32x4*)(dst + v * 8) = (f32x4){o[0], o[1], o[2], o[3]}; *(f32x4*)(dst + v * 8 + 4) = (f32x4){o[4], o[5], o[6], o[7]}; }
; }
; __device__ __forceinline__ void ffn_elementwise(const Ctx& C_, int l) {
;     ...
;     const int gw = C.bid * NWAVES + C.wave, NGW = C.G * NWAVES, lane = C.lane;
;     for (int it = gw; it < (NBATCH + DB) * 2; it += NGW) {
;         if (it < NBATCH * 2) { const int b = it / 2, i = it - b * 2;
;             row_bf16_to_f32(L_UP + (size_t)(b * LP + LP - 2 + i) * DUP, L_out + O_PFFN + ((size_t)(l * NBATCH + b) * 2 + i) * DUP, DUP, lane);
;         } else { const int k = it - NBATCH * 2, b = k / 2, i = k - b * 2;
;             row_bf16_to_f32(L_UP + (size_t)(MPROMPT + b * DS + 6 + i) * DUP, L_out + O_SFFN + ((size_t)(l * DB + b) * 2 + i) * DUP, DUP, lane); }
;     }
.LBB0_1185:
	v_ashrrev_i32_e32 v3, 31, v2
	s_mov_b32 s12, 0x1000
	s_mov_b32 s13, 0
	v_lshl_add_u64 v[6:7], v[2:3], 1, s[8:9]
	v_lshl_add_u64 v[14:15], v[2:3], 2, s[10:11]
	v_lshl_add_u64 v[16:17], v[6:7], 0, s[12:13]
	v_lshl_add_u64 v[18:19], v[16:17], 0, s[12:13]
	global_load_dwordx4 v[20:23], v[6:7], off
	global_load_dwordx4 v[24:27], v[6:7], off offset:1024
	global_load_dwordx4 v[28:31], v[6:7], off offset:2048
	global_load_dwordx4 v[32:35], v[6:7], off offset:3072
	global_load_dwordx4 v[36:39], v[16:17], off
	global_load_dwordx4 v[40:43], v[16:17], off offset:1024
	global_load_dwordx4 v[44:47], v[16:17], off offset:2048
	global_load_dwordx4 v[48:51], v[16:17], off offset:3072
	global_load_dwordx4 v[52:55], v[18:19], off
	global_load_dwordx4 v[56:59], v[18:19], off offset:1024
	global_load_dwordx4 v[60:63], v[18:19], off offset:2048
	v_lshl_add_u64 v[64:65], v[14:15], 0, s[12:13]
	v_lshl_add_u64 v[66:67], v[64:65], 0, s[12:13]
	v_lshl_add_u64 v[68:69], v[66:67], 0, s[12:13]
	v_lshl_add_u64 v[70:71], v[68:69], 0, s[12:13]
	v_lshl_add_u64 v[72:73], v[70:71], 0, s[12:13]
	s_waitcnt vmcnt(10)
	v_lshlrev_b32_e32 v76, 16, v20
	v_and_b32_e32 v77, 0xffff0000, v20
	v_lshlrev_b32_e32 v78, 16, v21
	v_and_b32_e32 v79, 0xffff0000, v21
	v_lshlrev_b32_e32 v80, 16, v22
	v_and_b32_e32 v81, 0xffff0000, v22
	v_lshlrev_b32_e32 v82, 16, v23
	v_and_b32_e32 v83, 0xffff0000, v23
	global_store_dwordx4 v[14:15], v[76:79], off
	global_store_dwordx4 v[14:15], v[80:83], off offset:16
	s_waitcnt vmcnt(11)
	v_lshlrev_b32_e32 v84, 16, v24
	v_and_b32_e32 v85, 0xffff0000, v24
	v_lshlrev_b32_e32 v86, 16, v25
	v_and_b32_e32 v87, 0xffff0000, v25
	v_lshlrev_b32_e32 v88, 16, v26
	v_and_b32_e32 v89, 0xffff0000, v26
	v_lshlrev_b32_e32 v90, 16, v27
	v_and_b32_e32 v91, 0xffff0000, v27
	global_store_dwordx4 v[14:15], v[84:87], off offset:2048
	global_store_dwordx4 v[14:15], v[88:91], off offset:2064
	s_waitcnt vmcnt(12)
	v_lshlrev_b32_e32 v76, 16, v28
	v_and_b32_e32 v77, 0xffff0000, v28
	v_lshlrev_b32_e32 v78, 16, v29
	v_and_b32_e32 v79, 0xffff0000, v29
	v_lshlrev_b32_e32 v80, 16, v30
	v_and_b32_e32 v81, 0xffff0000, v30
	v_lshlrev_b32_e32 v82, 16, v31
	v_and_b32_e32 v83, 0xffff0000, v31
	global_store_dwordx4 v[64:65], v[76:79], off
	global_store_dwordx4 v[64:65], v[80:83], off offset:16
	s_waitcnt vmcnt(13)
	v_lshlrev_b32_e32 v84, 16, v32
	v_and_b32_e32 v85, 0xffff0000, v32
	v_lshlrev_b32_e32 v86, 16, v33
	v_and_b32_e32 v87, 0xffff0000, v33
	v_lshlrev_b32_e32 v88, 16, v34
	v_and_b32_e32 v89, 0xffff0000, v34
	v_lshlrev_b32_e32 v90, 16, v35
	v_and_b32_e32 v91, 0xffff0000, v35
	global_store_dwordx4 v[64:65], v[84:87], off offset:2048
	global_store_dwordx4 v[64:65], v[88:91], off offset:2064
	s_waitcnt vmcnt(14)
	v_lshlrev_b32_e32 v76, 16, v36
	v_and_b32_e32 v77, 0xffff0000, v36
	v_lshlrev_b32_e32 v78, 16, v37
	v_and_b32_e32 v79, 0xffff0000, v37
	v_lshlrev_b32_e32 v80, 16, v38
	v_and_b32_e32 v81, 0xffff0000, v38
	v_lshlrev_b32_e32 v82, 16, v39
	v_and_b32_e32 v83, 0xffff0000, v39
	global_store_dwordx4 v[66:67], v[76:79], off
	global_store_dwordx4 v[66:67], v[80:83], off offset:16
	s_waitcnt vmcnt(15)
	v_lshlrev_b32_e32 v84, 16, v40
	v_and_b32_e32 v85, 0xffff0000, v40
	v_lshlrev_b32_e32 v86, 16, v41
	v_and_b32_e32 v87, 0xffff0000, v41
	v_lshlrev_b32_e32 v88, 16, v42
	v_and_b32_e32 v89, 0xffff0000, v42
	v_lshlrev_b32_e32 v90, 16, v43
	v_and_b32_e32 v91, 0xffff0000, v43
	global_store_dwordx4 v[66:67], v[84:87], off offset:2048
	global_store_dwordx4 v[66:67], v[88:91], off offset:2064
	s_waitcnt vmcnt(16)
	v_lshlrev_b32_e32 v76, 16, v44
	v_and_b32_e32 v77, 0xffff0000, v44
	v_lshlrev_b32_e32 v78, 16, v45
	v_and_b32_e32 v79, 0xffff0000, v45
	v_lshlrev_b32_e32 v80, 16, v46
	v_and_b32_e32 v81, 0xffff0000, v46
	v_lshlrev_b32_e32 v82, 16, v47
	v_and_b32_e32 v83, 0xffff0000, v47
	global_store_dwordx4 v[68:69], v[76:79], off
	global_store_dwordx4 v[68:69], v[80:83], off offset:16
	s_waitcnt vmcnt(17)
	v_lshlrev_b32_e32 v84, 16, v48
	v_and_b32_e32 v85, 0xffff0000, v48
	v_lshlrev_b32_e32 v86, 16, v49
	v_and_b32_e32 v87, 0xffff0000, v49
	v_lshlrev_b32_e32 v88, 16, v50
	v_and_b32_e32 v89, 0xffff0000, v50
	v_lshlrev_b32_e32 v90, 16, v51
	v_and_b32_e32 v91, 0xffff0000, v51
	global_store_dwordx4 v[68:69], v[84:87], off offset:2048
	global_store_dwordx4 v[68:69], v[88:91], off offset:2064
	s_waitcnt vmcnt(18)
	v_lshlrev_b32_e32 v76, 16, v52
	v_and_b32_e32 v77, 0xffff0000, v52
	v_lshlrev_b32_e32 v78, 16, v53
	v_and_b32_e32 v79, 0xffff0000, v53
	v_lshlrev_b32_e32 v80, 16, v54
	v_and_b32_e32 v81, 0xffff0000, v54
	v_lshlrev_b32_e32 v82, 16, v55
	v_and_b32_e32 v83, 0xffff0000, v55
	global_store_dwordx4 v[70:71], v[76:79], off
	global_store_dwordx4 v[70:71], v[80:83], off offset:16
	s_waitcnt vmcnt(19)
	v_lshlrev_b32_e32 v84, 16, v56
	v_and_b32_e32 v85, 0xffff0000, v56
	v_lshlrev_b32_e32 v86, 16, v57
	v_and_b32_e32 v87, 0xffff0000, v57
	v_lshlrev_b32_e32 v88, 16, v58
	v_and_b32_e32 v89, 0xffff0000, v58
	v_lshlrev_b32_e32 v90, 16, v59
	v_and_b32_e32 v91, 0xffff0000, v59
	global_store_dwordx4 v[70:71], v[84:87], off offset:2048
	global_store_dwordx4 v[70:71], v[88:91], off offset:2064
	s_waitcnt vmcnt(20)
	v_lshlrev_b32_e32 v76, 16, v60
	v_and_b32_e32 v77, 0xffff0000, v60
	v_lshlrev_b32_e32 v78, 16, v61
	v_and_b32_e32 v79, 0xffff0000, v61
	v_lshlrev_b32_e32 v80, 16, v62
	v_and_b32_e32 v81, 0xffff0000, v62
	v_lshlrev_b32_e32 v82, 16, v63
	v_and_b32_e32 v83, 0xffff0000, v63
	global_store_dwordx4 v[72:73], v[76:79], off
	global_store_dwordx4 v[72:73], v[80:83], off offset:16
	s_branch .LBB0_1175
